# per-block release-word grid barrier + hand-scheduled rmsnorm phases (all loads issued up front, counted waits)
# speedup vs baseline: 1.0363x; 1.0363x over previous
.LBB0_5:
	s_or_b64 exec, exec, s[0:1]
	s_cmp_ge_i32 s70, s71
	s_cbranch_scc1 .LBB0_474
	v_readlane_b32 s2, v240, 0
	s_lshl_b32 s6, s60, 3
	s_lshl_b32 s7, s2, 3
	s_lshl_b32 s58, s60, 5
	s_cmpk_lt_u32 s2, 0xc0
	s_cselect_b64 s[0:1], -1, 0
	v_writelane_b32 v240, s0, 7
	s_lshl_b32 s64, s60, 9
	v_lshrrev_b32_e32 v3, 20, v0
	v_writelane_b32 v240, s1, 8
	s_add_i32 s0, s60, s2
	s_lshl_b32 s1, s2, 9
	s_cmpk_lt_i32 s2, 0x100
	v_writelane_b32 v240, s1, 9
	s_cselect_b64 s[2:3], -1, 0
	v_writelane_b32 v240, s2, 10
	s_cmp_gt_i32 s71, -1
	v_lshrrev_b32_e32 v0, 10, v0
	v_writelane_b32 v240, s3, 11
	s_cselect_b64 s[2:3], -1, 0
	v_writelane_b32 v240, s2, 12
	v_or_b32_e32 v0, v0, v3
	v_mov_b32_e32 v165, 0
	v_writelane_b32 v240, s3, 13
	s_add_u32 s2, s68, 0x80200
	s_addc_u32 s3, s69, 0
	s_add_u32 s72, s68, 0x80400
	v_writelane_b32 v240, s2, 14
	s_addc_u32 s73, s69, 0
	v_mov_b32_e32 v190, 0x358637bd
	v_writelane_b32 v240, s3, 15
	s_add_u32 s2, s68, 0x80500
	s_addc_u32 s3, s69, 0
	v_writelane_b32 v240, s2, 16
	v_mov_b32_e32 v191, 0x260
	s_mov_b32 s62, 0x12000
	v_writelane_b32 v240, s3, 17
	s_add_u32 s2, s68, 0x80600
	s_addc_u32 s3, s69, 0
	v_writelane_b32 v240, s2, 18
	v_mov_b32_e32 v192, 0x3fcc422a
	v_mov_b32_e32 v193, 0x3c0881c4
	v_writelane_b32 v240, s3, 19
	s_add_u32 s2, s68, 0x80700
	s_addc_u32 s3, s69, 0
	v_writelane_b32 v240, s2, 20
	v_mov_b32_e32 v194, 0xbab64f3b
	v_mov_b32_e32 v195, 0x3ab69700
	v_writelane_b32 v240, s3, 21
	s_add_u32 s2, s68, 0x80800
	s_addc_u32 s3, s69, 0
	v_writelane_b32 v240, s2, 22
	v_mov_b32_e32 v196, 0x1000
	v_mov_b32_e32 v197, 0x2000
	v_writelane_b32 v240, s3, 23
	s_add_u32 s2, s68, 0x80900
	s_addc_u32 s3, s69, 0
	v_writelane_b32 v240, s2, 24
	v_mov_b32_e32 v198, 1
	v_mov_b32_e32 v199, 0x100
	v_writelane_b32 v240, s3, 25
	s_add_u32 s2, s68, 0x80a00
	s_addc_u32 s3, s69, 0
	v_writelane_b32 v240, s2, 26
	v_mov_b32_e32 v200, 0x7fffea00
	v_mov_b32_e32 v201, 0x7ffff800
	v_writelane_b32 v240, s3, 27
	s_add_u32 s2, s68, 0x80b00
	s_addc_u32 s3, s69, 0
	v_writelane_b32 v240, s2, 28
	v_mov_b32_e32 v202, 13
	v_mov_b32_e32 v203, 2
	v_writelane_b32 v240, s3, 29
	s_add_u32 s2, s68, 0x80c00
	s_addc_u32 s3, s69, 0
	v_writelane_b32 v240, s2, 30
	v_mov_b32_e32 v204, 6
	v_mov_b32_e32 v205, 0x7f800000
	v_writelane_b32 v240, s3, 31
	s_add_u32 s2, s68, 0x80d00
	s_addc_u32 s3, s69, 0
	v_writelane_b32 v240, s2, 32
	v_not_b32_e32 v206, 63
	v_not_b32_e32 v207, 31
	v_writelane_b32 v240, s3, 33
	s_add_u32 s2, s68, 0x80e00
	s_addc_u32 s3, s69, 0
	v_writelane_b32 v240, s2, 34
	v_mov_b32_e32 v208, 0x7fc00000
	v_mov_b32_e32 v209, 0x7f000000
	v_writelane_b32 v240, s3, 35
	s_add_u32 s2, s68, 0x80f00
	s_addc_u32 s3, s69, 0
	v_writelane_b32 v240, s2, 36
	s_movk_i32 s74, 0x6000
	s_mov_b32 s75, 0x18000
	v_writelane_b32 v240, s3, 37
	s_add_u32 s2, s68, 0x81000
	s_addc_u32 s3, s69, 0
	v_writelane_b32 v240, s2, 38
	s_mov_b32 s94, 0x1e000
	s_mov_b32 s95, 0xc000
	v_writelane_b32 v240, s3, 39
	s_add_u32 s2, s68, 0x81100
	s_addc_u32 s3, s69, 0
	v_writelane_b32 v240, s2, 40
	s_mov_b32 s63, 0x42000
	s_mov_b32 s92, 0x24000
	v_writelane_b32 v240, s3, 41
	s_add_u32 s2, s68, 0x81200
	s_addc_u32 s3, s69, 0
	v_writelane_b32 v240, s2, 42
	s_mov_b32 s93, 0x3c000
	s_mov_b32 s96, 0x60000
	v_writelane_b32 v240, s3, 43
	s_add_u32 s2, s68, 0x81300
	s_addc_u32 s3, s69, 0
	v_writelane_b32 v240, s2, 44
	s_movk_i32 s97, 0x100
	s_nop 0
	v_writelane_b32 v240, s3, 45
	s_add_u32 s2, s68, 0x83400
	s_addc_u32 s3, s69, 0
	v_writelane_b32 v240, s2, 46
	s_nop 1
	v_writelane_b32 v240, s3, 47
	s_add_u32 s2, s68, 0x83500
	s_addc_u32 s3, s69, 0
	s_abs_i32 s1, s60
	v_cvt_f32_u32_e32 v2, s1
	v_writelane_b32 v240, s2, 48
	s_mul_i32 s69, s60, 24
	v_rcp_iflag_f32_e32 v2, v2
	v_writelane_b32 v240, s3, 49
	s_mul_i32 s2, s61, s60
	v_readlane_b32 s10, v240, 1
	v_readlane_b32 s11, v240, 2
	s_load_dword s3, s[10:11], 0xf8
	v_mul_f32_e32 v2, 0x4f7ffffe, v2
	v_cvt_u32_f32_e32 v2, v2
	s_waitcnt lgkmcnt(0)
	s_mul_i32 s2, s2, s3
	v_writelane_b32 v240, s2, 50
	s_movk_i32 s2, 0x3ff
	v_and_or_b32 v0, v0, s2, v1
	s_sub_i32 s2, 0, s1
	v_readfirstlane_b32 s3, v2
	v_cvt_f32_u32_e32 v1, s60
	s_mul_i32 s2, s2, s3
	s_mul_hi_u32 s2, s3, s2
	s_add_i32 s3, s3, s2
	s_mul_hi_u32 s2, s3, 0xc0
	v_rcp_iflag_f32_e32 v1, v1
	s_mul_i32 s2, s2, s1
	s_sub_i32 s2, 0xc0, s2
	s_sub_i32 s5, s2, s1
	s_cmp_ge_u32 s2, s1
	v_mul_f32_e32 v1, 0x4f7ffffe, v1
	s_cselect_b32 s2, s5, s2
	v_cvt_u32_f32_e32 v1, v1
	s_sub_i32 s5, s2, s1
	s_cmp_ge_u32 s2, s1
	s_cselect_b32 s2, s5, s2
	s_sub_i32 s0, s0, s2
	s_sub_i32 s2, 0, s60
	v_readfirstlane_b32 s5, v1
	s_mul_i32 s2, s2, s5
	s_mul_hi_u32 s2, s5, s2
	s_add_i32 s5, s5, s2
	s_mul_hi_u32 s2, s0, s5
	s_mul_i32 s2, s2, s60
	s_sub_i32 s0, s0, s2
	s_sub_i32 s2, s0, s60
	s_cmp_ge_u32 s0, s60
	s_cselect_b32 s0, s2, s0
	s_sub_i32 s2, s0, s60
	s_cmp_ge_u32 s0, s60
	s_cselect_b32 s0, s2, s0
	s_lshl_b32 s0, s0, 3
	v_writelane_b32 v240, s0, 51
	s_mul_hi_u32 s0, s3, 0x2c0
	s_mul_i32 s0, s0, s1
	s_sub_i32 s0, 0x2c0, s0
	s_sub_i32 s2, s0, s1
	s_cmp_ge_u32 s0, s1
	s_cselect_b32 s0, s2, s0
	s_sub_i32 s2, s0, s1
	s_cmp_ge_u32 s0, s1
	s_cselect_b32 s0, s2, s0
	v_writelane_b32 v240, s0, 52
	s_sub_i32 s0, s60, s0
	s_lshl_b32 s0, s0, 3
	v_writelane_b32 v240, s0, 53
	s_lshl_b32 s0, s4, 2
	s_and_b32 s0, s0, 0xffffff00
	s_add_i32 s0, s0, 0
	v_writelane_b32 v240, s0, 54
	v_writelane_b32 v240, s8, 55
	v_writelane_b32 v240, s6, 56
	s_add_i32 s0, s7, s6
	v_writelane_b32 v240, s0, 57
	s_add_i32 s0, s7, 0xfffff000
	v_writelane_b32 v240, s0, 58
	s_add_i32 s0, 0, 0x20000
	v_writelane_b32 v240, s0, 59
	s_add_i32 s0, 0, 0x23fc0
	v_writelane_b32 v240, s0, 60
	s_add_i32 s0, 0, 0x23fc4
	v_writelane_b32 v240, s0, 61
	s_mov_b32 s1, 0
	v_writelane_b32 v240, s0, 62
	s_ashr_i32 s65, s64, 31
	s_ashr_i32 s59, s58, 31
	v_writelane_b32 v240, s1, 63
	v_cmp_eq_u32_e64 s[0:1], 0, v0
	s_mov_b32 s4, s60
	s_lshl_b32 s68, s60, 4
	v_writelane_b32 v239, s0, 0
	s_lshl_b32 s25, s60, 10
	s_lshl_b32 s24, s60, 12
	v_writelane_b32 v239, s1, 1
	s_lshl_b64 s[0:1], s[64:65], 2
	v_writelane_b32 v239, s0, 2
	s_mov_b32 s2, 0x30000
	s_nop 0
	v_writelane_b32 v239, s1, 3
	s_lshl_b64 s[0:1], s[64:65], 6
	v_writelane_b32 v239, s0, 4
	s_nop 1
	v_writelane_b32 v239, s1, 5
	s_lshl_b64 s[0:1], s[58:59], 11
	v_writelane_b32 v239, s0, 6
	s_nop 1
	v_writelane_b32 v239, s1, 7
	s_lshl_b64 s[0:1], s[58:59], 12
	v_writelane_b32 v239, s0, 8
	s_nop 1
	v_writelane_b32 v239, s1, 9
	v_writelane_b32 v239, s4, 10
	s_mov_b64 s[0:1], 0x80
	s_nop 0
	v_writelane_b32 v239, s5, 11
	v_writelane_b32 v239, s7, 12
	v_writelane_b32 v239, s58, 13
	s_nop 1
	v_writelane_b32 v239, s59, 14
	v_writelane_b32 v239, s68, 15
	v_writelane_b32 v239, s69, 16
	v_writelane_b32 v239, s72, 17
	s_nop 1
	v_writelane_b32 v239, s73, 18
	v_writelane_b32 v239, s25, 19
	v_writelane_b32 v239, s24, 20
	s_mov_b32 s101, 0
	s_branch .LBB0_11

.LBB0_11:
	v_readlane_b32 s4, v240, 1
	v_readlane_b32 s5, v240, 2
	s_load_dwordx2 s[6:7], s[4:5], 0xe0
	s_load_dwordx8 s[8:15], s[4:5], 0xc0
	v_readlane_b32 s3, v240, 0
	s_mov_b32 s78, s3
	v_mov_b32_e32 v0, v165
	s_waitcnt lgkmcnt(0)
	v_writelane_b32 v239, s8, 21
	v_mbcnt_lo_u32_b32 v0, -1, v0
	v_mbcnt_hi_u32_b32 v211, -1, v0
	v_writelane_b32 v239, s9, 22
	v_writelane_b32 v239, s10, 23
	v_writelane_b32 v239, s11, 24
	v_writelane_b32 v239, s12, 25
	v_writelane_b32 v239, s13, 26
	v_writelane_b32 v239, s14, 27
	v_writelane_b32 v239, s15, 28
	s_load_dwordx16 s[8:23], s[4:5], 0x0
	v_writelane_b32 v239, s6, 29
	v_readlane_b32 s3, v240, 55
	s_cmp_lt_i32 s70, 29
	v_writelane_b32 v239, s7, 30
	s_waitcnt lgkmcnt(0)
	v_writelane_b32 v239, s8, 31
	v_add_u32_e32 v210, s3, v211
	s_mov_b64 s[6:7], -1
	v_writelane_b32 v239, s9, 32
	v_writelane_b32 v239, s10, 33
	v_writelane_b32 v239, s11, 34
	v_writelane_b32 v239, s12, 35
	v_writelane_b32 v239, s13, 36
	v_writelane_b32 v239, s14, 37
	v_writelane_b32 v239, s15, 38
	v_writelane_b32 v239, s16, 39
	v_writelane_b32 v239, s17, 40
	v_writelane_b32 v239, s18, 41
	v_writelane_b32 v239, s19, 42
	v_writelane_b32 v239, s20, 43
	v_writelane_b32 v239, s21, 44
	v_writelane_b32 v239, s22, 45
	v_writelane_b32 v239, s23, 46
	s_load_dwordx16 s[16:31], s[4:5], 0x40
	s_load_dwordx16 s[36:51], s[4:5], 0x80
	s_mov_b64 s[12:13], 0
	s_mov_b64 s[4:5], 0
	s_cbranch_scc1 .LBB0_28
	s_cmp_eq_u32 s70, 29
	s_mov_b64 s[4:5], -1
	s_cbranch_scc0 .LBB0_32
	s_waitcnt lgkmcnt(0)
	v_readlane_b32 s34, v239, 29
	v_readlane_b32 s35, v239, 30
	v_readlane_b32 s14, v239, 25
	v_readlane_b32 s15, v239, 26
	v_and_b32_e32 v8, 63, v211
	v_lshlrev_b32_e32 v0, 5, v8
	v_lshlrev_b32_e32 v1, 4, v8
	v_lshlrev_b32_e32 v9, 2, v8
	v_xor_b32_e32 v2, 0x4, v9
	v_xor_b32_e32 v3, 0x8, v9
	v_xor_b32_e32 v4, 0x10, v9
	v_xor_b32_e32 v5, 0x20, v9
	v_xor_b32_e32 v6, 0x40, v9
	v_xor_b32_e32 v7, 0x80, v9
	v_readlane_b32 s3, v240, 55
	v_readlane_b32 s6, v239, 10
	s_lshr_b32 s3, s3, 6
	s_lshl_b32 s7, s78, 3
	s_add_i32 s3, s3, s7
	s_lshl_b32 s6, s6, 3
	s_cmpk_lt_i32 s3, 0x2000
	s_cbranch_scc0 .LnormF_end
.LnormF_loop:
	s_mov_b32 s8, s3
	s_add_i32 s9, s8, s6
	s_add_i32 s10, s9, s6
	s_add_i32 s11, s10, s6
	s_cmpk_lt_i32 s9, 0x2000
	s_cselect_b32 s9, s9, s3
	s_cmpk_lt_i32 s10, 0x2000
	s_cselect_b32 s10, s10, s3
	s_cmpk_lt_i32 s11, 0x2000
	s_cselect_b32 s11, s11, s3
	s_lshl_b32 s7, s8, 12
	s_add_u32 s4, s34, s7
	s_addc_u32 s5, s35, 0
	s_add_u32 s4, s4, 0x6900000
	s_addc_u32 s5, s5, 0
	global_load_dwordx4 v[16:19], v0, s[4:5]
	global_load_dwordx4 v[20:23], v0, s[4:5] offset:16
	global_load_dwordx4 v[24:27], v0, s[4:5] offset:2048
	global_load_dwordx4 v[28:31], v0, s[4:5] offset:2064
	s_lshl_b32 s7, s9, 12
	s_add_u32 s4, s34, s7
	s_addc_u32 s5, s35, 0
	s_add_u32 s4, s4, 0x6900000
	s_addc_u32 s5, s5, 0
	global_load_dwordx4 v[32:35], v0, s[4:5]
	global_load_dwordx4 v[36:39], v0, s[4:5] offset:16
	global_load_dwordx4 v[40:43], v0, s[4:5] offset:2048
	global_load_dwordx4 v[44:47], v0, s[4:5] offset:2064
	s_lshl_b32 s7, s10, 12
	s_add_u32 s4, s34, s7
	s_addc_u32 s5, s35, 0
	s_add_u32 s4, s4, 0x6900000
	s_addc_u32 s5, s5, 0
	global_load_dwordx4 v[48:51], v0, s[4:5]
	global_load_dwordx4 v[52:55], v0, s[4:5] offset:16
	global_load_dwordx4 v[56:59], v0, s[4:5] offset:2048
	global_load_dwordx4 v[60:63], v0, s[4:5] offset:2064
	s_lshl_b32 s7, s11, 12
	s_add_u32 s4, s34, s7
	s_addc_u32 s5, s35, 0
	s_add_u32 s4, s4, 0x6900000
	s_addc_u32 s5, s5, 0
	global_load_dwordx4 v[64:67], v0, s[4:5]
	global_load_dwordx4 v[68:71], v0, s[4:5] offset:16
	global_load_dwordx4 v[72:75], v0, s[4:5] offset:2048
	global_load_dwordx4 v[76:79], v0, s[4:5] offset:2064
	global_load_dwordx4 v[80:83], v0, s[14:15]
	global_load_dwordx4 v[84:87], v0, s[14:15] offset:16
	global_load_dwordx4 v[88:91], v0, s[14:15] offset:2048
	global_load_dwordx4 v[92:95], v0, s[14:15] offset:2064
	s_waitcnt vmcnt(16)
	v_mul_f32_e32 v160, v17, v17
	v_mul_f32_e32 v9, v19, v19
	v_fmac_f32_e32 v160, v16, v16
	v_fmac_f32_e32 v9, v18, v18
	v_add_f32_e32 v160, v160, v9
	v_mul_f32_e32 v8, v21, v21
	v_mul_f32_e32 v9, v23, v23
	v_fmac_f32_e32 v8, v20, v20
	v_fmac_f32_e32 v9, v22, v22
	v_add_f32_e32 v8, v8, v9
	v_add_f32_e32 v160, v160, v8
	v_mul_f32_e32 v8, v25, v25
	v_mul_f32_e32 v9, v27, v27
	v_fmac_f32_e32 v8, v24, v24
	v_fmac_f32_e32 v9, v26, v26
	v_add_f32_e32 v8, v8, v9
	v_add_f32_e32 v160, v160, v8
	v_mul_f32_e32 v8, v29, v29
	v_mul_f32_e32 v9, v31, v31
	v_fmac_f32_e32 v8, v28, v28
	v_fmac_f32_e32 v9, v30, v30
	v_add_f32_e32 v8, v8, v9
	v_add_f32_e32 v160, v160, v8
	s_waitcnt vmcnt(12)
	v_mul_f32_e32 v161, v33, v33
	v_mul_f32_e32 v9, v35, v35
	v_fmac_f32_e32 v161, v32, v32
	v_fmac_f32_e32 v9, v34, v34
	v_add_f32_e32 v161, v161, v9
	v_mul_f32_e32 v8, v37, v37
	v_mul_f32_e32 v9, v39, v39
	v_fmac_f32_e32 v8, v36, v36
	v_fmac_f32_e32 v9, v38, v38
	v_add_f32_e32 v8, v8, v9
	v_add_f32_e32 v161, v161, v8
	v_mul_f32_e32 v8, v41, v41
	v_mul_f32_e32 v9, v43, v43
	v_fmac_f32_e32 v8, v40, v40
	v_fmac_f32_e32 v9, v42, v42
	v_add_f32_e32 v8, v8, v9
	v_add_f32_e32 v161, v161, v8
	v_mul_f32_e32 v8, v45, v45
	v_mul_f32_e32 v9, v47, v47
	v_fmac_f32_e32 v8, v44, v44
	v_fmac_f32_e32 v9, v46, v46
	v_add_f32_e32 v8, v8, v9
	v_add_f32_e32 v161, v161, v8
	s_waitcnt vmcnt(8)
	v_mul_f32_e32 v162, v49, v49
	v_mul_f32_e32 v9, v51, v51
	v_fmac_f32_e32 v162, v48, v48
	v_fmac_f32_e32 v9, v50, v50
	v_add_f32_e32 v162, v162, v9
	v_mul_f32_e32 v8, v53, v53
	v_mul_f32_e32 v9, v55, v55
	v_fmac_f32_e32 v8, v52, v52
	v_fmac_f32_e32 v9, v54, v54
	v_add_f32_e32 v8, v8, v9
	v_add_f32_e32 v162, v162, v8
	v_mul_f32_e32 v8, v57, v57
	v_mul_f32_e32 v9, v59, v59
	v_fmac_f32_e32 v8, v56, v56
	v_fmac_f32_e32 v9, v58, v58
	v_add_f32_e32 v8, v8, v9
	v_add_f32_e32 v162, v162, v8
	v_mul_f32_e32 v8, v61, v61
	v_mul_f32_e32 v9, v63, v63
	v_fmac_f32_e32 v8, v60, v60
	v_fmac_f32_e32 v9, v62, v62
	v_add_f32_e32 v8, v8, v9
	v_add_f32_e32 v162, v162, v8
	s_waitcnt vmcnt(4)
	v_mul_f32_e32 v163, v65, v65
	v_mul_f32_e32 v9, v67, v67
	v_fmac_f32_e32 v163, v64, v64
	v_fmac_f32_e32 v9, v66, v66
	v_add_f32_e32 v163, v163, v9
	v_mul_f32_e32 v8, v69, v69
	v_mul_f32_e32 v9, v71, v71
	v_fmac_f32_e32 v8, v68, v68
	v_fmac_f32_e32 v9, v70, v70
	v_add_f32_e32 v8, v8, v9
	v_add_f32_e32 v163, v163, v8
	v_mul_f32_e32 v8, v73, v73
	v_mul_f32_e32 v9, v75, v75
	v_fmac_f32_e32 v8, v72, v72
	v_fmac_f32_e32 v9, v74, v74
	v_add_f32_e32 v8, v8, v9
	v_add_f32_e32 v163, v163, v8
	v_mul_f32_e32 v8, v77, v77
	v_mul_f32_e32 v9, v79, v79
	v_fmac_f32_e32 v8, v76, v76
	v_fmac_f32_e32 v9, v78, v78
	v_add_f32_e32 v8, v8, v9
	v_add_f32_e32 v163, v163, v8
	ds_bpermute_b32 v8, v2, v160
	ds_bpermute_b32 v9, v2, v161
	ds_bpermute_b32 v10, v2, v162
	ds_bpermute_b32 v11, v2, v163
	s_waitcnt lgkmcnt(3)
	v_add_f32_e32 v160, v160, v8
	s_waitcnt lgkmcnt(2)
	v_add_f32_e32 v161, v161, v9
	s_waitcnt lgkmcnt(1)
	v_add_f32_e32 v162, v162, v10
	s_waitcnt lgkmcnt(0)
	v_add_f32_e32 v163, v163, v11
	ds_bpermute_b32 v8, v3, v160
	ds_bpermute_b32 v9, v3, v161
	ds_bpermute_b32 v10, v3, v162
	ds_bpermute_b32 v11, v3, v163
	s_waitcnt lgkmcnt(3)
	v_add_f32_e32 v160, v160, v8
	s_waitcnt lgkmcnt(2)
	v_add_f32_e32 v161, v161, v9
	s_waitcnt lgkmcnt(1)
	v_add_f32_e32 v162, v162, v10
	s_waitcnt lgkmcnt(0)
	v_add_f32_e32 v163, v163, v11
	ds_bpermute_b32 v8, v4, v160
	ds_bpermute_b32 v9, v4, v161
	ds_bpermute_b32 v10, v4, v162
	ds_bpermute_b32 v11, v4, v163
	s_waitcnt lgkmcnt(3)
	v_add_f32_e32 v160, v160, v8
	s_waitcnt lgkmcnt(2)
	v_add_f32_e32 v161, v161, v9
	s_waitcnt lgkmcnt(1)
	v_add_f32_e32 v162, v162, v10
	s_waitcnt lgkmcnt(0)
	v_add_f32_e32 v163, v163, v11
	ds_bpermute_b32 v8, v5, v160
	ds_bpermute_b32 v9, v5, v161
	ds_bpermute_b32 v10, v5, v162
	ds_bpermute_b32 v11, v5, v163
	s_waitcnt lgkmcnt(3)
	v_add_f32_e32 v160, v160, v8
	s_waitcnt lgkmcnt(2)
	v_add_f32_e32 v161, v161, v9
	s_waitcnt lgkmcnt(1)
	v_add_f32_e32 v162, v162, v10
	s_waitcnt lgkmcnt(0)
	v_add_f32_e32 v163, v163, v11
	ds_bpermute_b32 v8, v6, v160
	ds_bpermute_b32 v9, v6, v161
	ds_bpermute_b32 v10, v6, v162
	ds_bpermute_b32 v11, v6, v163
	s_waitcnt lgkmcnt(3)
	v_add_f32_e32 v160, v160, v8
	s_waitcnt lgkmcnt(2)
	v_add_f32_e32 v161, v161, v9
	s_waitcnt lgkmcnt(1)
	v_add_f32_e32 v162, v162, v10
	s_waitcnt lgkmcnt(0)
	v_add_f32_e32 v163, v163, v11
	ds_bpermute_b32 v8, v7, v160
	ds_bpermute_b32 v9, v7, v161
	ds_bpermute_b32 v10, v7, v162
	ds_bpermute_b32 v11, v7, v163
	s_waitcnt lgkmcnt(3)
	v_add_f32_e32 v160, v160, v8
	s_waitcnt lgkmcnt(2)
	v_add_f32_e32 v161, v161, v9
	s_waitcnt lgkmcnt(1)
	v_add_f32_e32 v162, v162, v10
	s_waitcnt lgkmcnt(0)
	v_add_f32_e32 v163, v163, v11
	s_mov_b32 s7, 0xf800000
	v_fmamk_f32 v160, v160, 0x3a800000, v190
	v_mul_f32_e32 v8, 0x4f800000, v160
	v_cmp_gt_f32_e32 vcc, s7, v160
	s_nop 1
	v_cndmask_b32_e32 v160, v160, v8, vcc
	v_sqrt_f32_e32 v8, v160
	s_nop 0
	v_add_u32_e32 v9, -1, v8
	v_fma_f32 v10, -v9, v8, v160
	v_cmp_ge_f32_e64 s[4:5], 0, v10
	v_add_u32_e32 v10, 1, v8
	s_nop 0
	v_cndmask_b32_e64 v9, v8, v9, s[4:5]
	v_fma_f32 v8, -v10, v8, v160
	v_cmp_lt_f32_e64 s[4:5], 0, v8
	s_nop 1
	v_cndmask_b32_e64 v8, v9, v10, s[4:5]
	v_mul_f32_e32 v9, 0x37800000, v8
	v_cndmask_b32_e32 v8, v8, v9, vcc
	v_cmp_class_f32_e32 vcc, v160, v191
	s_nop 1
	v_cndmask_b32_e32 v160, v8, v160, vcc
	v_div_scale_f32 v8, s[4:5], v160, v160, 1.0
	v_rcp_f32_e32 v9, v8
	s_nop 0
	v_fma_f32 v10, -v8, v9, 1.0
	v_fmac_f32_e32 v9, v10, v9
	v_div_scale_f32 v10, vcc, 1.0, v160, 1.0
	v_mul_f32_e32 v11, v10, v9
	v_fma_f32 v12, -v8, v11, v10
	v_fmac_f32_e32 v11, v12, v9
	v_fma_f32 v8, -v8, v11, v10
	v_div_fmas_f32 v8, v8, v9, v11
	v_div_fixup_f32 v160, v8, v160, 1.0
	s_mov_b32 s7, 0xf800000
	v_fmamk_f32 v161, v161, 0x3a800000, v190
	v_mul_f32_e32 v8, 0x4f800000, v161
	v_cmp_gt_f32_e32 vcc, s7, v161
	s_nop 1
	v_cndmask_b32_e32 v161, v161, v8, vcc
	v_sqrt_f32_e32 v8, v161
	s_nop 0
	v_add_u32_e32 v9, -1, v8
	v_fma_f32 v10, -v9, v8, v161
	v_cmp_ge_f32_e64 s[4:5], 0, v10
	v_add_u32_e32 v10, 1, v8
	s_nop 0
	v_cndmask_b32_e64 v9, v8, v9, s[4:5]
	v_fma_f32 v8, -v10, v8, v161
	v_cmp_lt_f32_e64 s[4:5], 0, v8
	s_nop 1
	v_cndmask_b32_e64 v8, v9, v10, s[4:5]
	v_mul_f32_e32 v9, 0x37800000, v8
	v_cndmask_b32_e32 v8, v8, v9, vcc
	v_cmp_class_f32_e32 vcc, v161, v191
	s_nop 1
	v_cndmask_b32_e32 v161, v8, v161, vcc
	v_div_scale_f32 v8, s[4:5], v161, v161, 1.0
	v_rcp_f32_e32 v9, v8
	s_nop 0
	v_fma_f32 v10, -v8, v9, 1.0
	v_fmac_f32_e32 v9, v10, v9
	v_div_scale_f32 v10, vcc, 1.0, v161, 1.0
	v_mul_f32_e32 v11, v10, v9
	v_fma_f32 v12, -v8, v11, v10
	v_fmac_f32_e32 v11, v12, v9
	v_fma_f32 v8, -v8, v11, v10
	v_div_fmas_f32 v8, v8, v9, v11
	v_div_fixup_f32 v161, v8, v161, 1.0
	s_mov_b32 s7, 0xf800000
	v_fmamk_f32 v162, v162, 0x3a800000, v190
	v_mul_f32_e32 v8, 0x4f800000, v162
	v_cmp_gt_f32_e32 vcc, s7, v162
	s_nop 1
	v_cndmask_b32_e32 v162, v162, v8, vcc
	v_sqrt_f32_e32 v8, v162
	s_nop 0
	v_add_u32_e32 v9, -1, v8
	v_fma_f32 v10, -v9, v8, v162
	v_cmp_ge_f32_e64 s[4:5], 0, v10
	v_add_u32_e32 v10, 1, v8
	s_nop 0
	v_cndmask_b32_e64 v9, v8, v9, s[4:5]
	v_fma_f32 v8, -v10, v8, v162
	v_cmp_lt_f32_e64 s[4:5], 0, v8
	s_nop 1
	v_cndmask_b32_e64 v8, v9, v10, s[4:5]
	v_mul_f32_e32 v9, 0x37800000, v8
	v_cndmask_b32_e32 v8, v8, v9, vcc
	v_cmp_class_f32_e32 vcc, v162, v191
	s_nop 1
	v_cndmask_b32_e32 v162, v8, v162, vcc
	v_div_scale_f32 v8, s[4:5], v162, v162, 1.0
	v_rcp_f32_e32 v9, v8
	s_nop 0
	v_fma_f32 v10, -v8, v9, 1.0
	v_fmac_f32_e32 v9, v10, v9
	v_div_scale_f32 v10, vcc, 1.0, v162, 1.0
	v_mul_f32_e32 v11, v10, v9
	v_fma_f32 v12, -v8, v11, v10
	v_fmac_f32_e32 v11, v12, v9
	v_fma_f32 v8, -v8, v11, v10
	v_div_fmas_f32 v8, v8, v9, v11
	v_div_fixup_f32 v162, v8, v162, 1.0
	s_mov_b32 s7, 0xf800000
	v_fmamk_f32 v163, v163, 0x3a800000, v190
	v_mul_f32_e32 v8, 0x4f800000, v163
	v_cmp_gt_f32_e32 vcc, s7, v163
	s_nop 1
	v_cndmask_b32_e32 v163, v163, v8, vcc
	v_sqrt_f32_e32 v8, v163
	s_nop 0
	v_add_u32_e32 v9, -1, v8
	v_fma_f32 v10, -v9, v8, v163
	v_cmp_ge_f32_e64 s[4:5], 0, v10
	v_add_u32_e32 v10, 1, v8
	s_nop 0
	v_cndmask_b32_e64 v9, v8, v9, s[4:5]
	v_fma_f32 v8, -v10, v8, v163
	v_cmp_lt_f32_e64 s[4:5], 0, v8
	s_nop 1
	v_cndmask_b32_e64 v8, v9, v10, s[4:5]
	v_mul_f32_e32 v9, 0x37800000, v8
	v_cndmask_b32_e32 v8, v8, v9, vcc
	v_cmp_class_f32_e32 vcc, v163, v191
	s_nop 1
	v_cndmask_b32_e32 v163, v8, v163, vcc
	v_div_scale_f32 v8, s[4:5], v163, v163, 1.0
	v_rcp_f32_e32 v9, v8
	s_nop 0
	v_fma_f32 v10, -v8, v9, 1.0
	v_fmac_f32_e32 v9, v10, v9
	v_div_scale_f32 v10, vcc, 1.0, v163, 1.0
	v_mul_f32_e32 v11, v10, v9
	v_fma_f32 v12, -v8, v11, v10
	v_fmac_f32_e32 v11, v12, v9
	v_fma_f32 v8, -v8, v11, v10
	v_div_fmas_f32 v8, v8, v9, v11
	v_div_fixup_f32 v163, v8, v163, 1.0
	s_waitcnt vmcnt(0)
	v_readlane_b32 s4, v239, 27
	v_readlane_b32 s5, v239, 28
	s_lshl_b32 s7, s8, 12
	s_add_u32 s4, s4, s7
	s_addc_u32 s5, s5, 0
	v_mul_f32_e32 v16, v16, v160
	v_mul_f32_e32 v16, v80, v16
	v_mul_f32_e32 v17, v17, v160
	v_mul_f32_e32 v17, v81, v17
	v_mul_f32_e32 v18, v18, v160
	v_mul_f32_e32 v18, v82, v18
	v_mul_f32_e32 v19, v19, v160
	v_mul_f32_e32 v19, v83, v19
	global_store_dwordx4 v0, v[16:19], s[4:5]
	v_mul_f32_e32 v20, v20, v160
	v_mul_f32_e32 v20, v84, v20
	v_mul_f32_e32 v21, v21, v160
	v_mul_f32_e32 v21, v85, v21
	v_mul_f32_e32 v22, v22, v160
	v_mul_f32_e32 v22, v86, v22
	v_mul_f32_e32 v23, v23, v160
	v_mul_f32_e32 v23, v87, v23
	global_store_dwordx4 v0, v[20:23], s[4:5] offset:16
	v_mul_f32_e32 v24, v24, v160
	v_mul_f32_e32 v24, v88, v24
	v_mul_f32_e32 v25, v25, v160
	v_mul_f32_e32 v25, v89, v25
	v_mul_f32_e32 v26, v26, v160
	v_mul_f32_e32 v26, v90, v26
	v_mul_f32_e32 v27, v27, v160
	v_mul_f32_e32 v27, v91, v27
	global_store_dwordx4 v0, v[24:27], s[4:5] offset:2048
	v_mul_f32_e32 v28, v28, v160
	v_mul_f32_e32 v28, v92, v28
	v_mul_f32_e32 v29, v29, v160
	v_mul_f32_e32 v29, v93, v29
	v_mul_f32_e32 v30, v30, v160
	v_mul_f32_e32 v30, v94, v30
	v_mul_f32_e32 v31, v31, v160
	v_mul_f32_e32 v31, v95, v31
	global_store_dwordx4 v0, v[28:31], s[4:5] offset:2064
	v_readlane_b32 s4, v239, 27
	v_readlane_b32 s5, v239, 28
	s_lshl_b32 s7, s9, 12
	s_add_u32 s4, s4, s7
	s_addc_u32 s5, s5, 0
	v_mul_f32_e32 v32, v32, v161
	v_mul_f32_e32 v32, v80, v32
	v_mul_f32_e32 v33, v33, v161
	v_mul_f32_e32 v33, v81, v33
	v_mul_f32_e32 v34, v34, v161
	v_mul_f32_e32 v34, v82, v34
	v_mul_f32_e32 v35, v35, v161
	v_mul_f32_e32 v35, v83, v35
	global_store_dwordx4 v0, v[32:35], s[4:5]
	v_mul_f32_e32 v36, v36, v161
	v_mul_f32_e32 v36, v84, v36
	v_mul_f32_e32 v37, v37, v161
	v_mul_f32_e32 v37, v85, v37
	v_mul_f32_e32 v38, v38, v161
	v_mul_f32_e32 v38, v86, v38
	v_mul_f32_e32 v39, v39, v161
	v_mul_f32_e32 v39, v87, v39
	global_store_dwordx4 v0, v[36:39], s[4:5] offset:16
	v_mul_f32_e32 v40, v40, v161
	v_mul_f32_e32 v40, v88, v40
	v_mul_f32_e32 v41, v41, v161
	v_mul_f32_e32 v41, v89, v41
	v_mul_f32_e32 v42, v42, v161
	v_mul_f32_e32 v42, v90, v42
	v_mul_f32_e32 v43, v43, v161
	v_mul_f32_e32 v43, v91, v43
	global_store_dwordx4 v0, v[40:43], s[4:5] offset:2048
	v_mul_f32_e32 v44, v44, v161
	v_mul_f32_e32 v44, v92, v44
	v_mul_f32_e32 v45, v45, v161
	v_mul_f32_e32 v45, v93, v45
	v_mul_f32_e32 v46, v46, v161
	v_mul_f32_e32 v46, v94, v46
	v_mul_f32_e32 v47, v47, v161
	v_mul_f32_e32 v47, v95, v47
	global_store_dwordx4 v0, v[44:47], s[4:5] offset:2064
	v_readlane_b32 s4, v239, 27
	v_readlane_b32 s5, v239, 28
	s_lshl_b32 s7, s10, 12
	s_add_u32 s4, s4, s7
	s_addc_u32 s5, s5, 0
	v_mul_f32_e32 v48, v48, v162
	v_mul_f32_e32 v48, v80, v48
	v_mul_f32_e32 v49, v49, v162
	v_mul_f32_e32 v49, v81, v49
	v_mul_f32_e32 v50, v50, v162
	v_mul_f32_e32 v50, v82, v50
	v_mul_f32_e32 v51, v51, v162
	v_mul_f32_e32 v51, v83, v51
	global_store_dwordx4 v0, v[48:51], s[4:5]
	v_mul_f32_e32 v52, v52, v162
	v_mul_f32_e32 v52, v84, v52
	v_mul_f32_e32 v53, v53, v162
	v_mul_f32_e32 v53, v85, v53
	v_mul_f32_e32 v54, v54, v162
	v_mul_f32_e32 v54, v86, v54
	v_mul_f32_e32 v55, v55, v162
	v_mul_f32_e32 v55, v87, v55
	global_store_dwordx4 v0, v[52:55], s[4:5] offset:16
	v_mul_f32_e32 v56, v56, v162
	v_mul_f32_e32 v56, v88, v56
	v_mul_f32_e32 v57, v57, v162
	v_mul_f32_e32 v57, v89, v57
	v_mul_f32_e32 v58, v58, v162
	v_mul_f32_e32 v58, v90, v58
	v_mul_f32_e32 v59, v59, v162
	v_mul_f32_e32 v59, v91, v59
	global_store_dwordx4 v0, v[56:59], s[4:5] offset:2048
	v_mul_f32_e32 v60, v60, v162
	v_mul_f32_e32 v60, v92, v60
	v_mul_f32_e32 v61, v61, v162
	v_mul_f32_e32 v61, v93, v61
	v_mul_f32_e32 v62, v62, v162
	v_mul_f32_e32 v62, v94, v62
	v_mul_f32_e32 v63, v63, v162
	v_mul_f32_e32 v63, v95, v63
	global_store_dwordx4 v0, v[60:63], s[4:5] offset:2064
	v_readlane_b32 s4, v239, 27
	v_readlane_b32 s5, v239, 28
	s_lshl_b32 s7, s11, 12
	s_add_u32 s4, s4, s7
	s_addc_u32 s5, s5, 0
	v_mul_f32_e32 v64, v64, v163
	v_mul_f32_e32 v64, v80, v64
	v_mul_f32_e32 v65, v65, v163
	v_mul_f32_e32 v65, v81, v65
	v_mul_f32_e32 v66, v66, v163
	v_mul_f32_e32 v66, v82, v66
	v_mul_f32_e32 v67, v67, v163
	v_mul_f32_e32 v67, v83, v67
	global_store_dwordx4 v0, v[64:67], s[4:5]
	v_mul_f32_e32 v68, v68, v163
	v_mul_f32_e32 v68, v84, v68
	v_mul_f32_e32 v69, v69, v163
	v_mul_f32_e32 v69, v85, v69
	v_mul_f32_e32 v70, v70, v163
	v_mul_f32_e32 v70, v86, v70
	v_mul_f32_e32 v71, v71, v163
	v_mul_f32_e32 v71, v87, v71
	global_store_dwordx4 v0, v[68:71], s[4:5] offset:16
	v_mul_f32_e32 v72, v72, v163
	v_mul_f32_e32 v72, v88, v72
	v_mul_f32_e32 v73, v73, v163
	v_mul_f32_e32 v73, v89, v73
	v_mul_f32_e32 v74, v74, v163
	v_mul_f32_e32 v74, v90, v74
	v_mul_f32_e32 v75, v75, v163
	v_mul_f32_e32 v75, v91, v75
	global_store_dwordx4 v0, v[72:75], s[4:5] offset:2048
	v_mul_f32_e32 v76, v76, v163
	v_mul_f32_e32 v76, v92, v76
	v_mul_f32_e32 v77, v77, v163
	v_mul_f32_e32 v77, v93, v77
	v_mul_f32_e32 v78, v78, v163
	v_mul_f32_e32 v78, v94, v78
	v_mul_f32_e32 v79, v79, v163
	v_mul_f32_e32 v79, v95, v79
	global_store_dwordx4 v0, v[76:79], s[4:5] offset:2064
	s_lshl_b32 s7, s6, 2
	s_add_i32 s3, s3, s7
	s_cmpk_lt_i32 s3, 0x2000
	s_cbranch_scc1 .LnormF_loop
.LnormF_end:
	s_branch .LBB0_31
.LBB0_28:
	s_and_b64 vcc, exec, s[6:7]
	s_cbranch_vccz .LBB0_33
	s_cmp_lg_u32 s70, 0
	s_mov_b64 s[12:13], -1
	s_cselect_b64 s[4:5], -1, 0
	s_andn2_b64 vcc, exec, s[4:5]
	s_cbranch_vccz .LBB0_34
.LBB0_30:
	s_and_b64 vcc, exec, s[12:13]
	s_cbranch_vccnz .LBB0_349
	s_branch .LBB0_409
.LBB0_31:
	s_mov_b64 s[4:5], 0
.LBB0_32:
.LBB0_33:
	s_andn2_b64 vcc, exec, s[4:5]
	s_cbranch_vccnz .LBB0_30

.LBB0_82:
	v_readlane_b32 s34, v239, 29
	v_readlane_b32 s35, v239, 30
	s_and_b64 vcc, exec, s[4:5]
	s_cbranch_vccz .LBB0_99
	s_waitcnt lgkmcnt(0)
	s_lshl_b32 s7, s79, 12
	s_add_u32 s18, s18, s7
	s_addc_u32 s19, s19, 0
	v_readlane_b32 s14, v239, 51
	v_readlane_b32 s15, v239, 52
	v_and_b32_e32 v8, 63, v211
	v_lshlrev_b32_e32 v0, 5, v8
	v_lshlrev_b32_e32 v1, 4, v8
	v_lshlrev_b32_e32 v9, 2, v8
	v_xor_b32_e32 v2, 0x4, v9
	v_xor_b32_e32 v3, 0x8, v9
	v_xor_b32_e32 v4, 0x10, v9
	v_xor_b32_e32 v5, 0x20, v9
	v_xor_b32_e32 v6, 0x40, v9
	v_xor_b32_e32 v7, 0x80, v9
	v_readlane_b32 s3, v240, 55
	v_readlane_b32 s6, v239, 10
	s_lshr_b32 s3, s3, 6
	s_lshl_b32 s7, s78, 3
	s_add_i32 s3, s3, s7
	s_lshl_b32 s6, s6, 3
	s_cmpk_lt_i32 s3, 0x2000
	s_cbranch_scc0 .Lnorm2_end
.Lnorm2_loop:
	s_mov_b32 s8, s3
	s_add_i32 s9, s8, s6
	s_add_i32 s10, s9, s6
	s_add_i32 s11, s10, s6
	s_cmpk_lt_i32 s9, 0x2000
	s_cselect_b32 s9, s9, s3
	s_cmpk_lt_i32 s10, 0x2000
	s_cselect_b32 s10, s10, s3
	s_cmpk_lt_i32 s11, 0x2000
	s_cselect_b32 s11, s11, s3
	s_lshl_b32 s7, s8, 12
	s_add_u32 s4, s34, s7
	s_addc_u32 s5, s35, 0
	s_add_u32 s4, s4, 0x6900000
	s_addc_u32 s5, s5, 0
	global_load_dwordx4 v[16:19], v0, s[4:5]
	global_load_dwordx4 v[20:23], v0, s[4:5] offset:16
	global_load_dwordx4 v[24:27], v0, s[4:5] offset:2048
	global_load_dwordx4 v[28:31], v0, s[4:5] offset:2064
	s_lshl_b32 s7, s9, 12
	s_add_u32 s4, s34, s7
	s_addc_u32 s5, s35, 0
	s_add_u32 s4, s4, 0x6900000
	s_addc_u32 s5, s5, 0
	global_load_dwordx4 v[32:35], v0, s[4:5]
	global_load_dwordx4 v[36:39], v0, s[4:5] offset:16
	global_load_dwordx4 v[40:43], v0, s[4:5] offset:2048
	global_load_dwordx4 v[44:47], v0, s[4:5] offset:2064
	s_lshl_b32 s7, s10, 12
	s_add_u32 s4, s34, s7
	s_addc_u32 s5, s35, 0
	s_add_u32 s4, s4, 0x6900000
	s_addc_u32 s5, s5, 0
	global_load_dwordx4 v[48:51], v0, s[4:5]
	global_load_dwordx4 v[52:55], v0, s[4:5] offset:16
	global_load_dwordx4 v[56:59], v0, s[4:5] offset:2048
	global_load_dwordx4 v[60:63], v0, s[4:5] offset:2064
	s_lshl_b32 s7, s11, 12
	s_add_u32 s4, s34, s7
	s_addc_u32 s5, s35, 0
	s_add_u32 s4, s4, 0x6900000
	s_addc_u32 s5, s5, 0
	global_load_dwordx4 v[64:67], v0, s[4:5]
	global_load_dwordx4 v[68:71], v0, s[4:5] offset:16
	global_load_dwordx4 v[72:75], v0, s[4:5] offset:2048
	global_load_dwordx4 v[76:79], v0, s[4:5] offset:2064
	global_load_dwordx4 v[80:83], v0, s[18:19]
	global_load_dwordx4 v[84:87], v0, s[18:19] offset:16
	global_load_dwordx4 v[88:91], v0, s[18:19] offset:2048
	global_load_dwordx4 v[92:95], v0, s[18:19] offset:2064
	s_sub_i32 s7, s8, 0x1000
	s_lshr_b32 s7, s7, 11
	s_add_i32 s7, s7, 1
	s_cmpk_lt_i32 s8, 0x1000
	s_cselect_b32 s7, 0, s7
	s_mulk_i32 s7, 0x6000
	s_add_i32 s7, s7, 0x3000
	s_add_u32 s4, s14, s7
	s_addc_u32 s5, s15, 0
	global_load_dwordx4 v[112:115], v0, s[4:5]
	global_load_dwordx4 v[116:119], v0, s[4:5] offset:16
	global_load_dwordx4 v[120:123], v0, s[4:5] offset:2048
	global_load_dwordx4 v[124:127], v0, s[4:5] offset:2064
	s_add_u32 s4, s4, 0x1000
	s_addc_u32 s5, s5, 0
	global_load_dwordx4 v[96:99], v0, s[4:5]
	global_load_dwordx4 v[100:103], v0, s[4:5] offset:16
	global_load_dwordx4 v[104:107], v0, s[4:5] offset:2048
	global_load_dwordx4 v[108:111], v0, s[4:5] offset:2064
	s_sub_i32 s7, s9, 0x1000
	s_lshr_b32 s7, s7, 11
	s_add_i32 s7, s7, 1
	s_cmpk_lt_i32 s9, 0x1000
	s_cselect_b32 s7, 0, s7
	s_mulk_i32 s7, 0x6000
	s_add_i32 s7, s7, 0x3000
	s_add_u32 s4, s14, s7
	s_addc_u32 s5, s15, 0
	global_load_dwordx4 v[144:147], v0, s[4:5]
	global_load_dwordx4 v[148:151], v0, s[4:5] offset:16
	global_load_dwordx4 v[152:155], v0, s[4:5] offset:2048
	global_load_dwordx4 v[156:159], v0, s[4:5] offset:2064
	s_add_u32 s4, s4, 0x1000
	s_addc_u32 s5, s5, 0
	global_load_dwordx4 v[128:131], v0, s[4:5]
	global_load_dwordx4 v[132:135], v0, s[4:5] offset:16
	global_load_dwordx4 v[136:139], v0, s[4:5] offset:2048
	global_load_dwordx4 v[140:143], v0, s[4:5] offset:2064
	s_waitcnt vmcnt(32)
	v_mul_f32_e32 v160, v17, v17
	v_mul_f32_e32 v9, v19, v19
	v_fmac_f32_e32 v160, v16, v16
	v_fmac_f32_e32 v9, v18, v18
	v_add_f32_e32 v160, v160, v9
	v_mul_f32_e32 v8, v21, v21
	v_mul_f32_e32 v9, v23, v23
	v_fmac_f32_e32 v8, v20, v20
	v_fmac_f32_e32 v9, v22, v22
	v_add_f32_e32 v8, v8, v9
	v_add_f32_e32 v160, v160, v8
	v_mul_f32_e32 v8, v25, v25
	v_mul_f32_e32 v9, v27, v27
	v_fmac_f32_e32 v8, v24, v24
	v_fmac_f32_e32 v9, v26, v26
	v_add_f32_e32 v8, v8, v9
	v_add_f32_e32 v160, v160, v8
	v_mul_f32_e32 v8, v29, v29
	v_mul_f32_e32 v9, v31, v31
	v_fmac_f32_e32 v8, v28, v28
	v_fmac_f32_e32 v9, v30, v30
	v_add_f32_e32 v8, v8, v9
	v_add_f32_e32 v160, v160, v8
	s_waitcnt vmcnt(28)
	v_mul_f32_e32 v161, v33, v33
	v_mul_f32_e32 v9, v35, v35
	v_fmac_f32_e32 v161, v32, v32
	v_fmac_f32_e32 v9, v34, v34
	v_add_f32_e32 v161, v161, v9
	v_mul_f32_e32 v8, v37, v37
	v_mul_f32_e32 v9, v39, v39
	v_fmac_f32_e32 v8, v36, v36
	v_fmac_f32_e32 v9, v38, v38
	v_add_f32_e32 v8, v8, v9
	v_add_f32_e32 v161, v161, v8
	v_mul_f32_e32 v8, v41, v41
	v_mul_f32_e32 v9, v43, v43
	v_fmac_f32_e32 v8, v40, v40
	v_fmac_f32_e32 v9, v42, v42
	v_add_f32_e32 v8, v8, v9
	v_add_f32_e32 v161, v161, v8
	v_mul_f32_e32 v8, v45, v45
	v_mul_f32_e32 v9, v47, v47
	v_fmac_f32_e32 v8, v44, v44
	v_fmac_f32_e32 v9, v46, v46
	v_add_f32_e32 v8, v8, v9
	v_add_f32_e32 v161, v161, v8
	s_waitcnt vmcnt(24)
	v_mul_f32_e32 v162, v49, v49
	v_mul_f32_e32 v9, v51, v51
	v_fmac_f32_e32 v162, v48, v48
	v_fmac_f32_e32 v9, v50, v50
	v_add_f32_e32 v162, v162, v9
	v_mul_f32_e32 v8, v53, v53
	v_mul_f32_e32 v9, v55, v55
	v_fmac_f32_e32 v8, v52, v52
	v_fmac_f32_e32 v9, v54, v54
	v_add_f32_e32 v8, v8, v9
	v_add_f32_e32 v162, v162, v8
	v_mul_f32_e32 v8, v57, v57
	v_mul_f32_e32 v9, v59, v59
	v_fmac_f32_e32 v8, v56, v56
	v_fmac_f32_e32 v9, v58, v58
	v_add_f32_e32 v8, v8, v9
	v_add_f32_e32 v162, v162, v8
	v_mul_f32_e32 v8, v61, v61
	v_mul_f32_e32 v9, v63, v63
	v_fmac_f32_e32 v8, v60, v60
	v_fmac_f32_e32 v9, v62, v62
	v_add_f32_e32 v8, v8, v9
	v_add_f32_e32 v162, v162, v8
	s_waitcnt vmcnt(20)
	v_mul_f32_e32 v163, v65, v65
	v_mul_f32_e32 v9, v67, v67
	v_fmac_f32_e32 v163, v64, v64
	v_fmac_f32_e32 v9, v66, v66
	v_add_f32_e32 v163, v163, v9
	v_mul_f32_e32 v8, v69, v69
	v_mul_f32_e32 v9, v71, v71
	v_fmac_f32_e32 v8, v68, v68
	v_fmac_f32_e32 v9, v70, v70
	v_add_f32_e32 v8, v8, v9
	v_add_f32_e32 v163, v163, v8
	v_mul_f32_e32 v8, v73, v73
	v_mul_f32_e32 v9, v75, v75
	v_fmac_f32_e32 v8, v72, v72
	v_fmac_f32_e32 v9, v74, v74
	v_add_f32_e32 v8, v8, v9
	v_add_f32_e32 v163, v163, v8
	v_mul_f32_e32 v8, v77, v77
	v_mul_f32_e32 v9, v79, v79
	v_fmac_f32_e32 v8, v76, v76
	v_fmac_f32_e32 v9, v78, v78
	v_add_f32_e32 v8, v8, v9
	v_add_f32_e32 v163, v163, v8
	ds_bpermute_b32 v8, v2, v160
	ds_bpermute_b32 v9, v2, v161
	ds_bpermute_b32 v10, v2, v162
	ds_bpermute_b32 v11, v2, v163
	s_waitcnt lgkmcnt(3)
	v_add_f32_e32 v160, v160, v8
	s_waitcnt lgkmcnt(2)
	v_add_f32_e32 v161, v161, v9
	s_waitcnt lgkmcnt(1)
	v_add_f32_e32 v162, v162, v10
	s_waitcnt lgkmcnt(0)
	v_add_f32_e32 v163, v163, v11
	ds_bpermute_b32 v8, v3, v160
	ds_bpermute_b32 v9, v3, v161
	ds_bpermute_b32 v10, v3, v162
	ds_bpermute_b32 v11, v3, v163
	s_waitcnt lgkmcnt(3)
	v_add_f32_e32 v160, v160, v8
	s_waitcnt lgkmcnt(2)
	v_add_f32_e32 v161, v161, v9
	s_waitcnt lgkmcnt(1)
	v_add_f32_e32 v162, v162, v10
	s_waitcnt lgkmcnt(0)
	v_add_f32_e32 v163, v163, v11
	ds_bpermute_b32 v8, v4, v160
	ds_bpermute_b32 v9, v4, v161
	ds_bpermute_b32 v10, v4, v162
	ds_bpermute_b32 v11, v4, v163
	s_waitcnt lgkmcnt(3)
	v_add_f32_e32 v160, v160, v8
	s_waitcnt lgkmcnt(2)
	v_add_f32_e32 v161, v161, v9
	s_waitcnt lgkmcnt(1)
	v_add_f32_e32 v162, v162, v10
	s_waitcnt lgkmcnt(0)
	v_add_f32_e32 v163, v163, v11
	ds_bpermute_b32 v8, v5, v160
	ds_bpermute_b32 v9, v5, v161
	ds_bpermute_b32 v10, v5, v162
	ds_bpermute_b32 v11, v5, v163
	s_waitcnt lgkmcnt(3)
	v_add_f32_e32 v160, v160, v8
	s_waitcnt lgkmcnt(2)
	v_add_f32_e32 v161, v161, v9
	s_waitcnt lgkmcnt(1)
	v_add_f32_e32 v162, v162, v10
	s_waitcnt lgkmcnt(0)
	v_add_f32_e32 v163, v163, v11
	ds_bpermute_b32 v8, v6, v160
	ds_bpermute_b32 v9, v6, v161
	ds_bpermute_b32 v10, v6, v162
	ds_bpermute_b32 v11, v6, v163
	s_waitcnt lgkmcnt(3)
	v_add_f32_e32 v160, v160, v8
	s_waitcnt lgkmcnt(2)
	v_add_f32_e32 v161, v161, v9
	s_waitcnt lgkmcnt(1)
	v_add_f32_e32 v162, v162, v10
	s_waitcnt lgkmcnt(0)
	v_add_f32_e32 v163, v163, v11
	ds_bpermute_b32 v8, v7, v160
	ds_bpermute_b32 v9, v7, v161
	ds_bpermute_b32 v10, v7, v162
	ds_bpermute_b32 v11, v7, v163
	s_waitcnt lgkmcnt(3)
	v_add_f32_e32 v160, v160, v8
	s_waitcnt lgkmcnt(2)
	v_add_f32_e32 v161, v161, v9
	s_waitcnt lgkmcnt(1)
	v_add_f32_e32 v162, v162, v10
	s_waitcnt lgkmcnt(0)
	v_add_f32_e32 v163, v163, v11
	s_mov_b32 s7, 0xf800000
	v_fmamk_f32 v160, v160, 0x3a800000, v190
	v_mul_f32_e32 v8, 0x4f800000, v160
	v_cmp_gt_f32_e32 vcc, s7, v160
	s_nop 1
	v_cndmask_b32_e32 v160, v160, v8, vcc
	v_sqrt_f32_e32 v8, v160
	s_nop 0
	v_add_u32_e32 v9, -1, v8
	v_fma_f32 v10, -v9, v8, v160
	v_cmp_ge_f32_e64 s[4:5], 0, v10
	v_add_u32_e32 v10, 1, v8
	s_nop 0
	v_cndmask_b32_e64 v9, v8, v9, s[4:5]
	v_fma_f32 v8, -v10, v8, v160
	v_cmp_lt_f32_e64 s[4:5], 0, v8
	s_nop 1
	v_cndmask_b32_e64 v8, v9, v10, s[4:5]
	v_mul_f32_e32 v9, 0x37800000, v8
	v_cndmask_b32_e32 v8, v8, v9, vcc
	v_cmp_class_f32_e32 vcc, v160, v191
	s_nop 1
	v_cndmask_b32_e32 v160, v8, v160, vcc
	v_div_scale_f32 v8, s[4:5], v160, v160, 1.0
	v_rcp_f32_e32 v9, v8
	s_nop 0
	v_fma_f32 v10, -v8, v9, 1.0
	v_fmac_f32_e32 v9, v10, v9
	v_div_scale_f32 v10, vcc, 1.0, v160, 1.0
	v_mul_f32_e32 v11, v10, v9
	v_fma_f32 v12, -v8, v11, v10
	v_fmac_f32_e32 v11, v12, v9
	v_fma_f32 v8, -v8, v11, v10
	v_div_fmas_f32 v8, v8, v9, v11
	v_div_fixup_f32 v160, v8, v160, 1.0
	s_mov_b32 s7, 0xf800000
	v_fmamk_f32 v161, v161, 0x3a800000, v190
	v_mul_f32_e32 v8, 0x4f800000, v161
	v_cmp_gt_f32_e32 vcc, s7, v161
	s_nop 1
	v_cndmask_b32_e32 v161, v161, v8, vcc
	v_sqrt_f32_e32 v8, v161
	s_nop 0
	v_add_u32_e32 v9, -1, v8
	v_fma_f32 v10, -v9, v8, v161
	v_cmp_ge_f32_e64 s[4:5], 0, v10
	v_add_u32_e32 v10, 1, v8
	s_nop 0
	v_cndmask_b32_e64 v9, v8, v9, s[4:5]
	v_fma_f32 v8, -v10, v8, v161
	v_cmp_lt_f32_e64 s[4:5], 0, v8
	s_nop 1
	v_cndmask_b32_e64 v8, v9, v10, s[4:5]
	v_mul_f32_e32 v9, 0x37800000, v8
	v_cndmask_b32_e32 v8, v8, v9, vcc
	v_cmp_class_f32_e32 vcc, v161, v191
	s_nop 1
	v_cndmask_b32_e32 v161, v8, v161, vcc
	v_div_scale_f32 v8, s[4:5], v161, v161, 1.0
	v_rcp_f32_e32 v9, v8
	s_nop 0
	v_fma_f32 v10, -v8, v9, 1.0
	v_fmac_f32_e32 v9, v10, v9
	v_div_scale_f32 v10, vcc, 1.0, v161, 1.0
	v_mul_f32_e32 v11, v10, v9
	v_fma_f32 v12, -v8, v11, v10
	v_fmac_f32_e32 v11, v12, v9
	v_fma_f32 v8, -v8, v11, v10
	v_div_fmas_f32 v8, v8, v9, v11
	v_div_fixup_f32 v161, v8, v161, 1.0
	s_mov_b32 s7, 0xf800000
	v_fmamk_f32 v162, v162, 0x3a800000, v190
	v_mul_f32_e32 v8, 0x4f800000, v162
	v_cmp_gt_f32_e32 vcc, s7, v162
	s_nop 1
	v_cndmask_b32_e32 v162, v162, v8, vcc
	v_sqrt_f32_e32 v8, v162
	s_nop 0
	v_add_u32_e32 v9, -1, v8
	v_fma_f32 v10, -v9, v8, v162
	v_cmp_ge_f32_e64 s[4:5], 0, v10
	v_add_u32_e32 v10, 1, v8
	s_nop 0
	v_cndmask_b32_e64 v9, v8, v9, s[4:5]
	v_fma_f32 v8, -v10, v8, v162
	v_cmp_lt_f32_e64 s[4:5], 0, v8
	s_nop 1
	v_cndmask_b32_e64 v8, v9, v10, s[4:5]
	v_mul_f32_e32 v9, 0x37800000, v8
	v_cndmask_b32_e32 v8, v8, v9, vcc
	v_cmp_class_f32_e32 vcc, v162, v191
	s_nop 1
	v_cndmask_b32_e32 v162, v8, v162, vcc
	v_div_scale_f32 v8, s[4:5], v162, v162, 1.0
	v_rcp_f32_e32 v9, v8
	s_nop 0
	v_fma_f32 v10, -v8, v9, 1.0
	v_fmac_f32_e32 v9, v10, v9
	v_div_scale_f32 v10, vcc, 1.0, v162, 1.0
	v_mul_f32_e32 v11, v10, v9
	v_fma_f32 v12, -v8, v11, v10
	v_fmac_f32_e32 v11, v12, v9
	v_fma_f32 v8, -v8, v11, v10
	v_div_fmas_f32 v8, v8, v9, v11
	v_div_fixup_f32 v162, v8, v162, 1.0
	s_mov_b32 s7, 0xf800000
	v_fmamk_f32 v163, v163, 0x3a800000, v190
	v_mul_f32_e32 v8, 0x4f800000, v163
	v_cmp_gt_f32_e32 vcc, s7, v163
	s_nop 1
	v_cndmask_b32_e32 v163, v163, v8, vcc
	v_sqrt_f32_e32 v8, v163
	s_nop 0
	v_add_u32_e32 v9, -1, v8
	v_fma_f32 v10, -v9, v8, v163
	v_cmp_ge_f32_e64 s[4:5], 0, v10
	v_add_u32_e32 v10, 1, v8
	s_nop 0
	v_cndmask_b32_e64 v9, v8, v9, s[4:5]
	v_fma_f32 v8, -v10, v8, v163
	v_cmp_lt_f32_e64 s[4:5], 0, v8
	s_nop 1
	v_cndmask_b32_e64 v8, v9, v10, s[4:5]
	v_mul_f32_e32 v9, 0x37800000, v8
	v_cndmask_b32_e32 v8, v8, v9, vcc
	v_cmp_class_f32_e32 vcc, v163, v191
	s_nop 1
	v_cndmask_b32_e32 v163, v8, v163, vcc
	v_div_scale_f32 v8, s[4:5], v163, v163, 1.0
	v_rcp_f32_e32 v9, v8
	s_nop 0
	v_fma_f32 v10, -v8, v9, 1.0
	v_fmac_f32_e32 v9, v10, v9
	v_div_scale_f32 v10, vcc, 1.0, v163, 1.0
	v_mul_f32_e32 v11, v10, v9
	v_fma_f32 v12, -v8, v11, v10
	v_fmac_f32_e32 v11, v12, v9
	v_fma_f32 v8, -v8, v11, v10
	v_div_fmas_f32 v8, v8, v9, v11
	v_div_fixup_f32 v163, v8, v163, 1.0
	s_waitcnt vmcnt(8)
	s_lshl_b32 s7, s8, 11
	s_add_u32 s4, s34, s7
	s_addc_u32 s5, s35, 0
	s_add_u32 s4, s4, 0x8900000
	s_addc_u32 s5, s5, 0
	v_mul_f32_e32 v19, v19, v160
	v_mul_f32_e32 v19, v83, v19
	v_mul_f32_e32 v18, v18, v160
	v_mul_f32_e32 v18, v82, v18
	v_mul_f32_e32 v17, v17, v160
	v_mul_f32_e32 v17, v81, v17
	v_mul_f32_e32 v16, v16, v160
	v_mul_f32_e32 v16, v80, v16
	v_add_f32_e32 v11, 1.0, v99
	v_fma_f32 v19, v11, v19, v115
	v_add_f32_e32 v10, 1.0, v98
	v_fma_f32 v18, v10, v18, v114
	v_add_f32_e32 v9, 1.0, v97
	v_fma_f32 v17, v9, v17, v113
	v_add_f32_e32 v8, 1.0, v96
	v_fma_f32 v16, v8, v16, v112
	v_mul_f32_e32 v23, v23, v160
	v_mul_f32_e32 v23, v87, v23
	v_mul_f32_e32 v22, v22, v160
	v_mul_f32_e32 v22, v86, v22
	v_mul_f32_e32 v21, v21, v160
	v_mul_f32_e32 v21, v85, v21
	v_mul_f32_e32 v20, v20, v160
	v_mul_f32_e32 v20, v84, v20
	v_add_f32_e32 v11, 1.0, v103
	v_fma_f32 v23, v11, v23, v119
	v_add_f32_e32 v10, 1.0, v102
	v_fma_f32 v22, v10, v22, v118
	v_add_f32_e32 v9, 1.0, v101
	v_fma_f32 v21, v9, v21, v117
	v_add_f32_e32 v8, 1.0, v100
	v_fma_f32 v20, v8, v20, v116
	v_cvt_pk_bf16_f32 v16, v16, v17
	v_cvt_pk_bf16_f32 v17, v18, v19
	v_cvt_pk_bf16_f32 v18, v20, v21
	v_cvt_pk_bf16_f32 v19, v22, v23
	global_store_dwordx4 v1, v[16:19], s[4:5]
	v_mul_f32_e32 v27, v27, v160
	v_mul_f32_e32 v27, v91, v27
	v_mul_f32_e32 v26, v26, v160
	v_mul_f32_e32 v26, v90, v26
	v_mul_f32_e32 v25, v25, v160
	v_mul_f32_e32 v25, v89, v25
	v_mul_f32_e32 v24, v24, v160
	v_mul_f32_e32 v24, v88, v24
	v_add_f32_e32 v11, 1.0, v107
	v_fma_f32 v27, v11, v27, v123
	v_add_f32_e32 v10, 1.0, v106
	v_fma_f32 v26, v10, v26, v122
	v_add_f32_e32 v9, 1.0, v105
	v_fma_f32 v25, v9, v25, v121
	v_add_f32_e32 v8, 1.0, v104
	v_fma_f32 v24, v8, v24, v120
	v_mul_f32_e32 v31, v31, v160
	v_mul_f32_e32 v31, v95, v31
	v_mul_f32_e32 v30, v30, v160
	v_mul_f32_e32 v30, v94, v30
	v_mul_f32_e32 v29, v29, v160
	v_mul_f32_e32 v29, v93, v29
	v_mul_f32_e32 v28, v28, v160
	v_mul_f32_e32 v28, v92, v28
	v_add_f32_e32 v11, 1.0, v111
	v_fma_f32 v31, v11, v31, v127
	v_add_f32_e32 v10, 1.0, v110
	v_fma_f32 v30, v10, v30, v126
	v_add_f32_e32 v9, 1.0, v109
	v_fma_f32 v29, v9, v29, v125
	v_add_f32_e32 v8, 1.0, v108
	v_fma_f32 v28, v8, v28, v124
	v_cvt_pk_bf16_f32 v24, v24, v25
	v_cvt_pk_bf16_f32 v25, v26, v27
	v_cvt_pk_bf16_f32 v26, v28, v29
	v_cvt_pk_bf16_f32 v27, v30, v31
	global_store_dwordx4 v1, v[24:27], s[4:5] offset:1024
	s_sub_i32 s7, s10, 0x1000
	s_lshr_b32 s7, s7, 11
	s_add_i32 s7, s7, 1
	s_cmpk_lt_i32 s10, 0x1000
	s_cselect_b32 s7, 0, s7
	s_mulk_i32 s7, 0x6000
	s_add_i32 s7, s7, 0x3000
	s_add_u32 s4, s14, s7
	s_addc_u32 s5, s15, 0
	global_load_dwordx4 v[112:115], v0, s[4:5]
	global_load_dwordx4 v[116:119], v0, s[4:5] offset:16
	global_load_dwordx4 v[120:123], v0, s[4:5] offset:2048
	global_load_dwordx4 v[124:127], v0, s[4:5] offset:2064
	s_add_u32 s4, s4, 0x1000
	s_addc_u32 s5, s5, 0
	global_load_dwordx4 v[96:99], v0, s[4:5]
	global_load_dwordx4 v[100:103], v0, s[4:5] offset:16
	global_load_dwordx4 v[104:107], v0, s[4:5] offset:2048
	global_load_dwordx4 v[108:111], v0, s[4:5] offset:2064
	s_waitcnt vmcnt(10)
	s_lshl_b32 s7, s9, 11
	s_add_u32 s4, s34, s7
	s_addc_u32 s5, s35, 0
	s_add_u32 s4, s4, 0x8900000
	s_addc_u32 s5, s5, 0
	v_mul_f32_e32 v35, v35, v161
	v_mul_f32_e32 v35, v83, v35
	v_mul_f32_e32 v34, v34, v161
	v_mul_f32_e32 v34, v82, v34
	v_mul_f32_e32 v33, v33, v161
	v_mul_f32_e32 v33, v81, v33
	v_mul_f32_e32 v32, v32, v161
	v_mul_f32_e32 v32, v80, v32
	v_add_f32_e32 v11, 1.0, v131
	v_fma_f32 v35, v11, v35, v147
	v_add_f32_e32 v10, 1.0, v130
	v_fma_f32 v34, v10, v34, v146
	v_add_f32_e32 v9, 1.0, v129
	v_fma_f32 v33, v9, v33, v145
	v_add_f32_e32 v8, 1.0, v128
	v_fma_f32 v32, v8, v32, v144
	v_mul_f32_e32 v39, v39, v161
	v_mul_f32_e32 v39, v87, v39
	v_mul_f32_e32 v38, v38, v161
	v_mul_f32_e32 v38, v86, v38
	v_mul_f32_e32 v37, v37, v161
	v_mul_f32_e32 v37, v85, v37
	v_mul_f32_e32 v36, v36, v161
	v_mul_f32_e32 v36, v84, v36
	v_add_f32_e32 v11, 1.0, v135
	v_fma_f32 v39, v11, v39, v151
	v_add_f32_e32 v10, 1.0, v134
	v_fma_f32 v38, v10, v38, v150
	v_add_f32_e32 v9, 1.0, v133
	v_fma_f32 v37, v9, v37, v149
	v_add_f32_e32 v8, 1.0, v132
	v_fma_f32 v36, v8, v36, v148
	v_cvt_pk_bf16_f32 v32, v32, v33
	v_cvt_pk_bf16_f32 v33, v34, v35
	v_cvt_pk_bf16_f32 v34, v36, v37
	v_cvt_pk_bf16_f32 v35, v38, v39
	global_store_dwordx4 v1, v[32:35], s[4:5]
	v_mul_f32_e32 v43, v43, v161
	v_mul_f32_e32 v43, v91, v43
	v_mul_f32_e32 v42, v42, v161
	v_mul_f32_e32 v42, v90, v42
	v_mul_f32_e32 v41, v41, v161
	v_mul_f32_e32 v41, v89, v41
	v_mul_f32_e32 v40, v40, v161
	v_mul_f32_e32 v40, v88, v40
	v_add_f32_e32 v11, 1.0, v139
	v_fma_f32 v43, v11, v43, v155
	v_add_f32_e32 v10, 1.0, v138
	v_fma_f32 v42, v10, v42, v154
	v_add_f32_e32 v9, 1.0, v137
	v_fma_f32 v41, v9, v41, v153
	v_add_f32_e32 v8, 1.0, v136
	v_fma_f32 v40, v8, v40, v152
	v_mul_f32_e32 v47, v47, v161
	v_mul_f32_e32 v47, v95, v47
	v_mul_f32_e32 v46, v46, v161
	v_mul_f32_e32 v46, v94, v46
	v_mul_f32_e32 v45, v45, v161
	v_mul_f32_e32 v45, v93, v45
	v_mul_f32_e32 v44, v44, v161
	v_mul_f32_e32 v44, v92, v44
	v_add_f32_e32 v11, 1.0, v143
	v_fma_f32 v47, v11, v47, v159
	v_add_f32_e32 v10, 1.0, v142
	v_fma_f32 v46, v10, v46, v158
	v_add_f32_e32 v9, 1.0, v141
	v_fma_f32 v45, v9, v45, v157
	v_add_f32_e32 v8, 1.0, v140
	v_fma_f32 v44, v8, v44, v156
	v_cvt_pk_bf16_f32 v40, v40, v41
	v_cvt_pk_bf16_f32 v41, v42, v43
	v_cvt_pk_bf16_f32 v42, v44, v45
	v_cvt_pk_bf16_f32 v43, v46, v47
	global_store_dwordx4 v1, v[40:43], s[4:5] offset:1024
	s_sub_i32 s7, s11, 0x1000
	s_lshr_b32 s7, s7, 11
	s_add_i32 s7, s7, 1
	s_cmpk_lt_i32 s11, 0x1000
	s_cselect_b32 s7, 0, s7
	s_mulk_i32 s7, 0x6000
	s_add_i32 s7, s7, 0x3000
	s_add_u32 s4, s14, s7
	s_addc_u32 s5, s15, 0
	global_load_dwordx4 v[144:147], v0, s[4:5]
	global_load_dwordx4 v[148:151], v0, s[4:5] offset:16
	global_load_dwordx4 v[152:155], v0, s[4:5] offset:2048
	global_load_dwordx4 v[156:159], v0, s[4:5] offset:2064
	s_add_u32 s4, s4, 0x1000
	s_addc_u32 s5, s5, 0
	global_load_dwordx4 v[128:131], v0, s[4:5]
	global_load_dwordx4 v[132:135], v0, s[4:5] offset:16
	global_load_dwordx4 v[136:139], v0, s[4:5] offset:2048
	global_load_dwordx4 v[140:143], v0, s[4:5] offset:2064
	s_waitcnt vmcnt(10)
	s_lshl_b32 s7, s10, 11
	s_add_u32 s4, s34, s7
	s_addc_u32 s5, s35, 0
	s_add_u32 s4, s4, 0x8900000
	s_addc_u32 s5, s5, 0
	v_mul_f32_e32 v51, v51, v162
	v_mul_f32_e32 v51, v83, v51
	v_mul_f32_e32 v50, v50, v162
	v_mul_f32_e32 v50, v82, v50
	v_mul_f32_e32 v49, v49, v162
	v_mul_f32_e32 v49, v81, v49
	v_mul_f32_e32 v48, v48, v162
	v_mul_f32_e32 v48, v80, v48
	v_add_f32_e32 v11, 1.0, v99
	v_fma_f32 v51, v11, v51, v115
	v_add_f32_e32 v10, 1.0, v98
	v_fma_f32 v50, v10, v50, v114
	v_add_f32_e32 v9, 1.0, v97
	v_fma_f32 v49, v9, v49, v113
	v_add_f32_e32 v8, 1.0, v96
	v_fma_f32 v48, v8, v48, v112
	v_mul_f32_e32 v55, v55, v162
	v_mul_f32_e32 v55, v87, v55
	v_mul_f32_e32 v54, v54, v162
	v_mul_f32_e32 v54, v86, v54
	v_mul_f32_e32 v53, v53, v162
	v_mul_f32_e32 v53, v85, v53
	v_mul_f32_e32 v52, v52, v162
	v_mul_f32_e32 v52, v84, v52
	v_add_f32_e32 v11, 1.0, v103
	v_fma_f32 v55, v11, v55, v119
	v_add_f32_e32 v10, 1.0, v102
	v_fma_f32 v54, v10, v54, v118
	v_add_f32_e32 v9, 1.0, v101
	v_fma_f32 v53, v9, v53, v117
	v_add_f32_e32 v8, 1.0, v100
	v_fma_f32 v52, v8, v52, v116
	v_cvt_pk_bf16_f32 v48, v48, v49
	v_cvt_pk_bf16_f32 v49, v50, v51
	v_cvt_pk_bf16_f32 v50, v52, v53
	v_cvt_pk_bf16_f32 v51, v54, v55
	global_store_dwordx4 v1, v[48:51], s[4:5]
	v_mul_f32_e32 v59, v59, v162
	v_mul_f32_e32 v59, v91, v59
	v_mul_f32_e32 v58, v58, v162
	v_mul_f32_e32 v58, v90, v58
	v_mul_f32_e32 v57, v57, v162
	v_mul_f32_e32 v57, v89, v57
	v_mul_f32_e32 v56, v56, v162
	v_mul_f32_e32 v56, v88, v56
	v_add_f32_e32 v11, 1.0, v107
	v_fma_f32 v59, v11, v59, v123
	v_add_f32_e32 v10, 1.0, v106
	v_fma_f32 v58, v10, v58, v122
	v_add_f32_e32 v9, 1.0, v105
	v_fma_f32 v57, v9, v57, v121
	v_add_f32_e32 v8, 1.0, v104
	v_fma_f32 v56, v8, v56, v120
	v_mul_f32_e32 v63, v63, v162
	v_mul_f32_e32 v63, v95, v63
	v_mul_f32_e32 v62, v62, v162
	v_mul_f32_e32 v62, v94, v62
	v_mul_f32_e32 v61, v61, v162
	v_mul_f32_e32 v61, v93, v61
	v_mul_f32_e32 v60, v60, v162
	v_mul_f32_e32 v60, v92, v60
	v_add_f32_e32 v11, 1.0, v111
	v_fma_f32 v63, v11, v63, v127
	v_add_f32_e32 v10, 1.0, v110
	v_fma_f32 v62, v10, v62, v126
	v_add_f32_e32 v9, 1.0, v109
	v_fma_f32 v61, v9, v61, v125
	v_add_f32_e32 v8, 1.0, v108
	v_fma_f32 v60, v8, v60, v124
	v_cvt_pk_bf16_f32 v56, v56, v57
	v_cvt_pk_bf16_f32 v57, v58, v59
	v_cvt_pk_bf16_f32 v58, v60, v61
	v_cvt_pk_bf16_f32 v59, v62, v63
	global_store_dwordx4 v1, v[56:59], s[4:5] offset:1024
	s_waitcnt vmcnt(2)
	s_lshl_b32 s7, s11, 11
	s_add_u32 s4, s34, s7
	s_addc_u32 s5, s35, 0
	s_add_u32 s4, s4, 0x8900000
	s_addc_u32 s5, s5, 0
	v_mul_f32_e32 v67, v67, v163
	v_mul_f32_e32 v67, v83, v67
	v_mul_f32_e32 v66, v66, v163
	v_mul_f32_e32 v66, v82, v66
	v_mul_f32_e32 v65, v65, v163
	v_mul_f32_e32 v65, v81, v65
	v_mul_f32_e32 v64, v64, v163
	v_mul_f32_e32 v64, v80, v64
	v_add_f32_e32 v11, 1.0, v131
	v_fma_f32 v67, v11, v67, v147
	v_add_f32_e32 v10, 1.0, v130
	v_fma_f32 v66, v10, v66, v146
	v_add_f32_e32 v9, 1.0, v129
	v_fma_f32 v65, v9, v65, v145
	v_add_f32_e32 v8, 1.0, v128
	v_fma_f32 v64, v8, v64, v144
	v_mul_f32_e32 v71, v71, v163
	v_mul_f32_e32 v71, v87, v71
	v_mul_f32_e32 v70, v70, v163
	v_mul_f32_e32 v70, v86, v70
	v_mul_f32_e32 v69, v69, v163
	v_mul_f32_e32 v69, v85, v69
	v_mul_f32_e32 v68, v68, v163
	v_mul_f32_e32 v68, v84, v68
	v_add_f32_e32 v11, 1.0, v135
	v_fma_f32 v71, v11, v71, v151
	v_add_f32_e32 v10, 1.0, v134
	v_fma_f32 v70, v10, v70, v150
	v_add_f32_e32 v9, 1.0, v133
	v_fma_f32 v69, v9, v69, v149
	v_add_f32_e32 v8, 1.0, v132
	v_fma_f32 v68, v8, v68, v148
	v_cvt_pk_bf16_f32 v64, v64, v65
	v_cvt_pk_bf16_f32 v65, v66, v67
	v_cvt_pk_bf16_f32 v66, v68, v69
	v_cvt_pk_bf16_f32 v67, v70, v71
	global_store_dwordx4 v1, v[64:67], s[4:5]
	v_mul_f32_e32 v75, v75, v163
	v_mul_f32_e32 v75, v91, v75
	v_mul_f32_e32 v74, v74, v163
	v_mul_f32_e32 v74, v90, v74
	v_mul_f32_e32 v73, v73, v163
	v_mul_f32_e32 v73, v89, v73
	v_mul_f32_e32 v72, v72, v163
	v_mul_f32_e32 v72, v88, v72
	v_add_f32_e32 v11, 1.0, v139
	v_fma_f32 v75, v11, v75, v155
	v_add_f32_e32 v10, 1.0, v138
	v_fma_f32 v74, v10, v74, v154
	v_add_f32_e32 v9, 1.0, v137
	v_fma_f32 v73, v9, v73, v153
	v_add_f32_e32 v8, 1.0, v136
	v_fma_f32 v72, v8, v72, v152
	v_mul_f32_e32 v79, v79, v163
	v_mul_f32_e32 v79, v95, v79
	v_mul_f32_e32 v78, v78, v163
	v_mul_f32_e32 v78, v94, v78
	v_mul_f32_e32 v77, v77, v163
	v_mul_f32_e32 v77, v93, v77
	v_mul_f32_e32 v76, v76, v163
	v_mul_f32_e32 v76, v92, v76
	v_add_f32_e32 v11, 1.0, v143
	v_fma_f32 v79, v11, v79, v159
	v_add_f32_e32 v10, 1.0, v142
	v_fma_f32 v78, v10, v78, v158
	v_add_f32_e32 v9, 1.0, v141
	v_fma_f32 v77, v9, v77, v157
	v_add_f32_e32 v8, 1.0, v140
	v_fma_f32 v76, v8, v76, v156
	v_cvt_pk_bf16_f32 v72, v72, v73
	v_cvt_pk_bf16_f32 v73, v74, v75
	v_cvt_pk_bf16_f32 v74, v76, v77
	v_cvt_pk_bf16_f32 v75, v78, v79
	global_store_dwordx4 v1, v[72:75], s[4:5] offset:1024
	s_lshl_b32 s7, s6, 2
	s_add_i32 s3, s3, s7
	s_cmpk_lt_i32 s3, 0x2000
	s_cbranch_scc1 .Lnorm2_loop
.Lnorm2_end:
.LBB0_98:
.LBB0_99:
	s_branch .LBB0_159

.LBB0_293:
	v_readlane_b32 s72, v239, 17
	s_andn2_b64 vcc, exec, s[66:67]
	v_readlane_b32 s73, v239, 18
	s_cbranch_vccnz .LBB0_348
	s_waitcnt lgkmcnt(0)
	v_readlane_b32 s46, v239, 29
	v_readlane_b32 s47, v239, 30
	s_lshl_b32 s7, s79, 12
	s_add_u32 s16, s16, s7
	s_addc_u32 s17, s17, 0
	v_readlane_b32 s14, v239, 51
	v_readlane_b32 s15, v239, 52
	s_add_i32 s3, s70, 5
	s_cmp_lt_u32 s3, 13
	s_cbranch_scc0 .Lnorm1_regular
	v_readlane_b32 s18, v239, 31
	v_readlane_b32 s19, v239, 32
	v_readlane_b32 s34, v239, 33
	v_readlane_b32 s35, v239, 34
	v_and_b32_e32 v8, 63, v211
	v_lshlrev_b32_e32 v0, 5, v8
	v_lshlrev_b32_e32 v1, 4, v8
	v_lshlrev_b32_e32 v9, 2, v8
	v_xor_b32_e32 v2, 0x4, v9
	v_xor_b32_e32 v3, 0x8, v9
	v_xor_b32_e32 v4, 0x10, v9
	v_xor_b32_e32 v5, 0x20, v9
	v_xor_b32_e32 v6, 0x40, v9
	v_xor_b32_e32 v7, 0x80, v9
	v_readlane_b32 s3, v240, 55
	v_readlane_b32 s6, v239, 10
	s_lshr_b32 s3, s3, 6
	s_lshl_b32 s7, s78, 3
	s_add_i32 s3, s3, s7
	s_lshl_b32 s6, s6, 3
	s_cmpk_lt_i32 s3, 0x2000
	s_cbranch_scc0 .Lnorm1f_end
.Lnorm1f_loop:
	s_mov_b32 s8, s3
	s_add_i32 s9, s8, s6
	s_add_i32 s10, s9, s6
	s_add_i32 s11, s10, s6
	s_cmpk_lt_i32 s9, 0x2000
	s_cselect_b32 s9, s9, s3
	s_cmpk_lt_i32 s10, 0x2000
	s_cselect_b32 s10, s10, s3
	s_cmpk_lt_i32 s11, 0x2000
	s_cselect_b32 s11, s11, s3
	s_cmpk_lt_i32 s8, 0x1000
	s_cselect_b32 s4, s18, s34
	s_cselect_b32 s5, s19, s35
	s_and_b32 s7, s8, 0xfff
	s_lshl_b32 s7, s7, 12
	s_add_u32 s4, s4, s7
	s_addc_u32 s5, s5, 0
	global_load_dwordx4 v[16:19], v0, s[4:5] nt
	global_load_dwordx4 v[20:23], v0, s[4:5] offset:16 nt
	global_load_dwordx4 v[24:27], v0, s[4:5] offset:2048 nt
	global_load_dwordx4 v[28:31], v0, s[4:5] offset:2064 nt
	s_cmpk_lt_i32 s9, 0x1000
	s_cselect_b32 s4, s18, s34
	s_cselect_b32 s5, s19, s35
	s_and_b32 s7, s9, 0xfff
	s_lshl_b32 s7, s7, 12
	s_add_u32 s4, s4, s7
	s_addc_u32 s5, s5, 0
	global_load_dwordx4 v[32:35], v0, s[4:5] nt
	global_load_dwordx4 v[36:39], v0, s[4:5] offset:16 nt
	global_load_dwordx4 v[40:43], v0, s[4:5] offset:2048 nt
	global_load_dwordx4 v[44:47], v0, s[4:5] offset:2064 nt
	s_cmpk_lt_i32 s10, 0x1000
	s_cselect_b32 s4, s18, s34
	s_cselect_b32 s5, s19, s35
	s_and_b32 s7, s10, 0xfff
	s_lshl_b32 s7, s7, 12
	s_add_u32 s4, s4, s7
	s_addc_u32 s5, s5, 0
	global_load_dwordx4 v[48:51], v0, s[4:5] nt
	global_load_dwordx4 v[52:55], v0, s[4:5] offset:16 nt
	global_load_dwordx4 v[56:59], v0, s[4:5] offset:2048 nt
	global_load_dwordx4 v[60:63], v0, s[4:5] offset:2064 nt
	s_cmpk_lt_i32 s11, 0x1000
	s_cselect_b32 s4, s18, s34
	s_cselect_b32 s5, s19, s35
	s_and_b32 s7, s11, 0xfff
	s_lshl_b32 s7, s7, 12
	s_add_u32 s4, s4, s7
	s_addc_u32 s5, s5, 0
	global_load_dwordx4 v[64:67], v0, s[4:5] nt
	global_load_dwordx4 v[68:71], v0, s[4:5] offset:16 nt
	global_load_dwordx4 v[72:75], v0, s[4:5] offset:2048 nt
	global_load_dwordx4 v[76:79], v0, s[4:5] offset:2064 nt
	global_load_dwordx4 v[80:83], v0, s[16:17]
	global_load_dwordx4 v[84:87], v0, s[16:17] offset:16
	global_load_dwordx4 v[88:91], v0, s[16:17] offset:2048
	global_load_dwordx4 v[92:95], v0, s[16:17] offset:2064
	s_sub_i32 s7, s8, 0x1000
	s_lshr_b32 s7, s7, 11
	s_add_i32 s7, s7, 1
	s_cmpk_lt_i32 s8, 0x1000
	s_cselect_b32 s7, 0, s7
	s_mulk_i32 s7, 0x6000
	s_add_i32 s7, s7, 0x0
	s_add_u32 s4, s14, s7
	s_addc_u32 s5, s15, 0
	global_load_dwordx4 v[112:115], v0, s[4:5]
	global_load_dwordx4 v[116:119], v0, s[4:5] offset:16
	global_load_dwordx4 v[120:123], v0, s[4:5] offset:2048
	global_load_dwordx4 v[124:127], v0, s[4:5] offset:2064
	s_add_u32 s4, s4, 0x1000
	s_addc_u32 s5, s5, 0
	global_load_dwordx4 v[96:99], v0, s[4:5]
	global_load_dwordx4 v[100:103], v0, s[4:5] offset:16
	global_load_dwordx4 v[104:107], v0, s[4:5] offset:2048
	global_load_dwordx4 v[108:111], v0, s[4:5] offset:2064
	s_sub_i32 s7, s9, 0x1000
	s_lshr_b32 s7, s7, 11
	s_add_i32 s7, s7, 1
	s_cmpk_lt_i32 s9, 0x1000
	s_cselect_b32 s7, 0, s7
	s_mulk_i32 s7, 0x6000
	s_add_i32 s7, s7, 0x0
	s_add_u32 s4, s14, s7
	s_addc_u32 s5, s15, 0
	global_load_dwordx4 v[144:147], v0, s[4:5]
	global_load_dwordx4 v[148:151], v0, s[4:5] offset:16
	global_load_dwordx4 v[152:155], v0, s[4:5] offset:2048
	global_load_dwordx4 v[156:159], v0, s[4:5] offset:2064
	s_add_u32 s4, s4, 0x1000
	s_addc_u32 s5, s5, 0
	global_load_dwordx4 v[128:131], v0, s[4:5]
	global_load_dwordx4 v[132:135], v0, s[4:5] offset:16
	global_load_dwordx4 v[136:139], v0, s[4:5] offset:2048
	global_load_dwordx4 v[140:143], v0, s[4:5] offset:2064
	s_waitcnt vmcnt(32)
	s_lshl_b32 s7, s8, 12
	s_add_u32 s4, s46, s7
	s_addc_u32 s5, s47, 0
	s_add_u32 s4, s4, 0x6900000
	s_addc_u32 s5, s5, 0
	global_store_dwordx4 v0, v[16:19], s[4:5]
	global_store_dwordx4 v0, v[20:23], s[4:5] offset:16
	global_store_dwordx4 v0, v[24:27], s[4:5] offset:2048
	global_store_dwordx4 v0, v[28:31], s[4:5] offset:2064
	v_mul_f32_e32 v160, v17, v17
	v_mul_f32_e32 v9, v19, v19
	v_fmac_f32_e32 v160, v16, v16
	v_fmac_f32_e32 v9, v18, v18
	v_add_f32_e32 v160, v160, v9
	v_mul_f32_e32 v8, v21, v21
	v_mul_f32_e32 v9, v23, v23
	v_fmac_f32_e32 v8, v20, v20
	v_fmac_f32_e32 v9, v22, v22
	v_add_f32_e32 v8, v8, v9
	v_add_f32_e32 v160, v160, v8
	v_mul_f32_e32 v8, v25, v25
	v_mul_f32_e32 v9, v27, v27
	v_fmac_f32_e32 v8, v24, v24
	v_fmac_f32_e32 v9, v26, v26
	v_add_f32_e32 v8, v8, v9
	v_add_f32_e32 v160, v160, v8
	v_mul_f32_e32 v8, v29, v29
	v_mul_f32_e32 v9, v31, v31
	v_fmac_f32_e32 v8, v28, v28
	v_fmac_f32_e32 v9, v30, v30
	v_add_f32_e32 v8, v8, v9
	v_add_f32_e32 v160, v160, v8
	s_waitcnt vmcnt(32)
	s_lshl_b32 s7, s9, 12
	s_add_u32 s4, s46, s7
	s_addc_u32 s5, s47, 0
	s_add_u32 s4, s4, 0x6900000
	s_addc_u32 s5, s5, 0
	global_store_dwordx4 v0, v[32:35], s[4:5]
	global_store_dwordx4 v0, v[36:39], s[4:5] offset:16
	global_store_dwordx4 v0, v[40:43], s[4:5] offset:2048
	global_store_dwordx4 v0, v[44:47], s[4:5] offset:2064
	v_mul_f32_e32 v161, v33, v33
	v_mul_f32_e32 v9, v35, v35
	v_fmac_f32_e32 v161, v32, v32
	v_fmac_f32_e32 v9, v34, v34
	v_add_f32_e32 v161, v161, v9
	v_mul_f32_e32 v8, v37, v37
	v_mul_f32_e32 v9, v39, v39
	v_fmac_f32_e32 v8, v36, v36
	v_fmac_f32_e32 v9, v38, v38
	v_add_f32_e32 v8, v8, v9
	v_add_f32_e32 v161, v161, v8
	v_mul_f32_e32 v8, v41, v41
	v_mul_f32_e32 v9, v43, v43
	v_fmac_f32_e32 v8, v40, v40
	v_fmac_f32_e32 v9, v42, v42
	v_add_f32_e32 v8, v8, v9
	v_add_f32_e32 v161, v161, v8
	v_mul_f32_e32 v8, v45, v45
	v_mul_f32_e32 v9, v47, v47
	v_fmac_f32_e32 v8, v44, v44
	v_fmac_f32_e32 v9, v46, v46
	v_add_f32_e32 v8, v8, v9
	v_add_f32_e32 v161, v161, v8
	s_waitcnt vmcnt(32)
	s_lshl_b32 s7, s10, 12
	s_add_u32 s4, s46, s7
	s_addc_u32 s5, s47, 0
	s_add_u32 s4, s4, 0x6900000
	s_addc_u32 s5, s5, 0
	global_store_dwordx4 v0, v[48:51], s[4:5]
	global_store_dwordx4 v0, v[52:55], s[4:5] offset:16
	global_store_dwordx4 v0, v[56:59], s[4:5] offset:2048
	global_store_dwordx4 v0, v[60:63], s[4:5] offset:2064
	v_mul_f32_e32 v162, v49, v49
	v_mul_f32_e32 v9, v51, v51
	v_fmac_f32_e32 v162, v48, v48
	v_fmac_f32_e32 v9, v50, v50
	v_add_f32_e32 v162, v162, v9
	v_mul_f32_e32 v8, v53, v53
	v_mul_f32_e32 v9, v55, v55
	v_fmac_f32_e32 v8, v52, v52
	v_fmac_f32_e32 v9, v54, v54
	v_add_f32_e32 v8, v8, v9
	v_add_f32_e32 v162, v162, v8
	v_mul_f32_e32 v8, v57, v57
	v_mul_f32_e32 v9, v59, v59
	v_fmac_f32_e32 v8, v56, v56
	v_fmac_f32_e32 v9, v58, v58
	v_add_f32_e32 v8, v8, v9
	v_add_f32_e32 v162, v162, v8
	v_mul_f32_e32 v8, v61, v61
	v_mul_f32_e32 v9, v63, v63
	v_fmac_f32_e32 v8, v60, v60
	v_fmac_f32_e32 v9, v62, v62
	v_add_f32_e32 v8, v8, v9
	v_add_f32_e32 v162, v162, v8
	s_waitcnt vmcnt(32)
	s_lshl_b32 s7, s11, 12
	s_add_u32 s4, s46, s7
	s_addc_u32 s5, s47, 0
	s_add_u32 s4, s4, 0x6900000
	s_addc_u32 s5, s5, 0
	global_store_dwordx4 v0, v[64:67], s[4:5]
	global_store_dwordx4 v0, v[68:71], s[4:5] offset:16
	global_store_dwordx4 v0, v[72:75], s[4:5] offset:2048
	global_store_dwordx4 v0, v[76:79], s[4:5] offset:2064
	v_mul_f32_e32 v163, v65, v65
	v_mul_f32_e32 v9, v67, v67
	v_fmac_f32_e32 v163, v64, v64
	v_fmac_f32_e32 v9, v66, v66
	v_add_f32_e32 v163, v163, v9
	v_mul_f32_e32 v8, v69, v69
	v_mul_f32_e32 v9, v71, v71
	v_fmac_f32_e32 v8, v68, v68
	v_fmac_f32_e32 v9, v70, v70
	v_add_f32_e32 v8, v8, v9
	v_add_f32_e32 v163, v163, v8
	v_mul_f32_e32 v8, v73, v73
	v_mul_f32_e32 v9, v75, v75
	v_fmac_f32_e32 v8, v72, v72
	v_fmac_f32_e32 v9, v74, v74
	v_add_f32_e32 v8, v8, v9
	v_add_f32_e32 v163, v163, v8
	v_mul_f32_e32 v8, v77, v77
	v_mul_f32_e32 v9, v79, v79
	v_fmac_f32_e32 v8, v76, v76
	v_fmac_f32_e32 v9, v78, v78
	v_add_f32_e32 v8, v8, v9
	v_add_f32_e32 v163, v163, v8
	ds_bpermute_b32 v8, v2, v160
	ds_bpermute_b32 v9, v2, v161
	ds_bpermute_b32 v10, v2, v162
	ds_bpermute_b32 v11, v2, v163
	s_waitcnt lgkmcnt(3)
	v_add_f32_e32 v160, v160, v8
	s_waitcnt lgkmcnt(2)
	v_add_f32_e32 v161, v161, v9
	s_waitcnt lgkmcnt(1)
	v_add_f32_e32 v162, v162, v10
	s_waitcnt lgkmcnt(0)
	v_add_f32_e32 v163, v163, v11
	ds_bpermute_b32 v8, v3, v160
	ds_bpermute_b32 v9, v3, v161
	ds_bpermute_b32 v10, v3, v162
	ds_bpermute_b32 v11, v3, v163
	s_waitcnt lgkmcnt(3)
	v_add_f32_e32 v160, v160, v8
	s_waitcnt lgkmcnt(2)
	v_add_f32_e32 v161, v161, v9
	s_waitcnt lgkmcnt(1)
	v_add_f32_e32 v162, v162, v10
	s_waitcnt lgkmcnt(0)
	v_add_f32_e32 v163, v163, v11
	ds_bpermute_b32 v8, v4, v160
	ds_bpermute_b32 v9, v4, v161
	ds_bpermute_b32 v10, v4, v162
	ds_bpermute_b32 v11, v4, v163
	s_waitcnt lgkmcnt(3)
	v_add_f32_e32 v160, v160, v8
	s_waitcnt lgkmcnt(2)
	v_add_f32_e32 v161, v161, v9
	s_waitcnt lgkmcnt(1)
	v_add_f32_e32 v162, v162, v10
	s_waitcnt lgkmcnt(0)
	v_add_f32_e32 v163, v163, v11
	ds_bpermute_b32 v8, v5, v160
	ds_bpermute_b32 v9, v5, v161
	ds_bpermute_b32 v10, v5, v162
	ds_bpermute_b32 v11, v5, v163
	s_waitcnt lgkmcnt(3)
	v_add_f32_e32 v160, v160, v8
	s_waitcnt lgkmcnt(2)
	v_add_f32_e32 v161, v161, v9
	s_waitcnt lgkmcnt(1)
	v_add_f32_e32 v162, v162, v10
	s_waitcnt lgkmcnt(0)
	v_add_f32_e32 v163, v163, v11
	ds_bpermute_b32 v8, v6, v160
	ds_bpermute_b32 v9, v6, v161
	ds_bpermute_b32 v10, v6, v162
	ds_bpermute_b32 v11, v6, v163
	s_waitcnt lgkmcnt(3)
	v_add_f32_e32 v160, v160, v8
	s_waitcnt lgkmcnt(2)
	v_add_f32_e32 v161, v161, v9
	s_waitcnt lgkmcnt(1)
	v_add_f32_e32 v162, v162, v10
	s_waitcnt lgkmcnt(0)
	v_add_f32_e32 v163, v163, v11
	ds_bpermute_b32 v8, v7, v160
	ds_bpermute_b32 v9, v7, v161
	ds_bpermute_b32 v10, v7, v162
	ds_bpermute_b32 v11, v7, v163
	s_waitcnt lgkmcnt(3)
	v_add_f32_e32 v160, v160, v8
	s_waitcnt lgkmcnt(2)
	v_add_f32_e32 v161, v161, v9
	s_waitcnt lgkmcnt(1)
	v_add_f32_e32 v162, v162, v10
	s_waitcnt lgkmcnt(0)
	v_add_f32_e32 v163, v163, v11
	s_mov_b32 s7, 0xf800000
	v_fmamk_f32 v160, v160, 0x3a800000, v190
	v_mul_f32_e32 v8, 0x4f800000, v160
	v_cmp_gt_f32_e32 vcc, s7, v160
	s_nop 1
	v_cndmask_b32_e32 v160, v160, v8, vcc
	v_sqrt_f32_e32 v8, v160
	s_nop 0
	v_add_u32_e32 v9, -1, v8
	v_fma_f32 v10, -v9, v8, v160
	v_cmp_ge_f32_e64 s[4:5], 0, v10
	v_add_u32_e32 v10, 1, v8
	s_nop 0
	v_cndmask_b32_e64 v9, v8, v9, s[4:5]
	v_fma_f32 v8, -v10, v8, v160
	v_cmp_lt_f32_e64 s[4:5], 0, v8
	s_nop 1
	v_cndmask_b32_e64 v8, v9, v10, s[4:5]
	v_mul_f32_e32 v9, 0x37800000, v8
	v_cndmask_b32_e32 v8, v8, v9, vcc
	v_cmp_class_f32_e32 vcc, v160, v191
	s_nop 1
	v_cndmask_b32_e32 v160, v8, v160, vcc
	v_div_scale_f32 v8, s[4:5], v160, v160, 1.0
	v_rcp_f32_e32 v9, v8
	s_nop 0
	v_fma_f32 v10, -v8, v9, 1.0
	v_fmac_f32_e32 v9, v10, v9
	v_div_scale_f32 v10, vcc, 1.0, v160, 1.0
	v_mul_f32_e32 v11, v10, v9
	v_fma_f32 v12, -v8, v11, v10
	v_fmac_f32_e32 v11, v12, v9
	v_fma_f32 v8, -v8, v11, v10
	v_div_fmas_f32 v8, v8, v9, v11
	v_div_fixup_f32 v160, v8, v160, 1.0
	s_mov_b32 s7, 0xf800000
	v_fmamk_f32 v161, v161, 0x3a800000, v190
	v_mul_f32_e32 v8, 0x4f800000, v161
	v_cmp_gt_f32_e32 vcc, s7, v161
	s_nop 1
	v_cndmask_b32_e32 v161, v161, v8, vcc
	v_sqrt_f32_e32 v8, v161
	s_nop 0
	v_add_u32_e32 v9, -1, v8
	v_fma_f32 v10, -v9, v8, v161
	v_cmp_ge_f32_e64 s[4:5], 0, v10
	v_add_u32_e32 v10, 1, v8
	s_nop 0
	v_cndmask_b32_e64 v9, v8, v9, s[4:5]
	v_fma_f32 v8, -v10, v8, v161
	v_cmp_lt_f32_e64 s[4:5], 0, v8
	s_nop 1
	v_cndmask_b32_e64 v8, v9, v10, s[4:5]
	v_mul_f32_e32 v9, 0x37800000, v8
	v_cndmask_b32_e32 v8, v8, v9, vcc
	v_cmp_class_f32_e32 vcc, v161, v191
	s_nop 1
	v_cndmask_b32_e32 v161, v8, v161, vcc
	v_div_scale_f32 v8, s[4:5], v161, v161, 1.0
	v_rcp_f32_e32 v9, v8
	s_nop 0
	v_fma_f32 v10, -v8, v9, 1.0
	v_fmac_f32_e32 v9, v10, v9
	v_div_scale_f32 v10, vcc, 1.0, v161, 1.0
	v_mul_f32_e32 v11, v10, v9
	v_fma_f32 v12, -v8, v11, v10
	v_fmac_f32_e32 v11, v12, v9
	v_fma_f32 v8, -v8, v11, v10
	v_div_fmas_f32 v8, v8, v9, v11
	v_div_fixup_f32 v161, v8, v161, 1.0
	s_mov_b32 s7, 0xf800000
	v_fmamk_f32 v162, v162, 0x3a800000, v190
	v_mul_f32_e32 v8, 0x4f800000, v162
	v_cmp_gt_f32_e32 vcc, s7, v162
	s_nop 1
	v_cndmask_b32_e32 v162, v162, v8, vcc
	v_sqrt_f32_e32 v8, v162
	s_nop 0
	v_add_u32_e32 v9, -1, v8
	v_fma_f32 v10, -v9, v8, v162
	v_cmp_ge_f32_e64 s[4:5], 0, v10
	v_add_u32_e32 v10, 1, v8
	s_nop 0
	v_cndmask_b32_e64 v9, v8, v9, s[4:5]
	v_fma_f32 v8, -v10, v8, v162
	v_cmp_lt_f32_e64 s[4:5], 0, v8
	s_nop 1
	v_cndmask_b32_e64 v8, v9, v10, s[4:5]
	v_mul_f32_e32 v9, 0x37800000, v8
	v_cndmask_b32_e32 v8, v8, v9, vcc
	v_cmp_class_f32_e32 vcc, v162, v191
	s_nop 1
	v_cndmask_b32_e32 v162, v8, v162, vcc
	v_div_scale_f32 v8, s[4:5], v162, v162, 1.0
	v_rcp_f32_e32 v9, v8
	s_nop 0
	v_fma_f32 v10, -v8, v9, 1.0
	v_fmac_f32_e32 v9, v10, v9
	v_div_scale_f32 v10, vcc, 1.0, v162, 1.0
	v_mul_f32_e32 v11, v10, v9
	v_fma_f32 v12, -v8, v11, v10
	v_fmac_f32_e32 v11, v12, v9
	v_fma_f32 v8, -v8, v11, v10
	v_div_fmas_f32 v8, v8, v9, v11
	v_div_fixup_f32 v162, v8, v162, 1.0
	s_mov_b32 s7, 0xf800000
	v_fmamk_f32 v163, v163, 0x3a800000, v190
	v_mul_f32_e32 v8, 0x4f800000, v163
	v_cmp_gt_f32_e32 vcc, s7, v163
	s_nop 1
	v_cndmask_b32_e32 v163, v163, v8, vcc
	v_sqrt_f32_e32 v8, v163
	s_nop 0
	v_add_u32_e32 v9, -1, v8
	v_fma_f32 v10, -v9, v8, v163
	v_cmp_ge_f32_e64 s[4:5], 0, v10
	v_add_u32_e32 v10, 1, v8
	s_nop 0
	v_cndmask_b32_e64 v9, v8, v9, s[4:5]
	v_fma_f32 v8, -v10, v8, v163
	v_cmp_lt_f32_e64 s[4:5], 0, v8
	s_nop 1
	v_cndmask_b32_e64 v8, v9, v10, s[4:5]
	v_mul_f32_e32 v9, 0x37800000, v8
	v_cndmask_b32_e32 v8, v8, v9, vcc
	v_cmp_class_f32_e32 vcc, v163, v191
	s_nop 1
	v_cndmask_b32_e32 v163, v8, v163, vcc
	v_div_scale_f32 v8, s[4:5], v163, v163, 1.0
	v_rcp_f32_e32 v9, v8
	s_nop 0
	v_fma_f32 v10, -v8, v9, 1.0
	v_fmac_f32_e32 v9, v10, v9
	v_div_scale_f32 v10, vcc, 1.0, v163, 1.0
	v_mul_f32_e32 v11, v10, v9
	v_fma_f32 v12, -v8, v11, v10
	v_fmac_f32_e32 v11, v12, v9
	v_fma_f32 v8, -v8, v11, v10
	v_div_fmas_f32 v8, v8, v9, v11
	v_div_fixup_f32 v163, v8, v163, 1.0
	s_waitcnt vmcnt(24)
	s_lshl_b32 s7, s8, 11
	s_add_u32 s4, s46, s7
	s_addc_u32 s5, s47, 0
	s_add_u32 s4, s4, 0x8900000
	s_addc_u32 s5, s5, 0
	v_mul_f32_e32 v19, v19, v160
	v_mul_f32_e32 v19, v83, v19
	v_mul_f32_e32 v18, v18, v160
	v_mul_f32_e32 v18, v82, v18
	v_mul_f32_e32 v17, v17, v160
	v_mul_f32_e32 v17, v81, v17
	v_mul_f32_e32 v16, v16, v160
	v_mul_f32_e32 v16, v80, v16
	v_add_f32_e32 v11, 1.0, v99
	v_fma_f32 v19, v11, v19, v115
	v_add_f32_e32 v10, 1.0, v98
	v_fma_f32 v18, v10, v18, v114
	v_add_f32_e32 v9, 1.0, v97
	v_fma_f32 v17, v9, v17, v113
	v_add_f32_e32 v8, 1.0, v96
	v_fma_f32 v16, v8, v16, v112
	v_mul_f32_e32 v23, v23, v160
	v_mul_f32_e32 v23, v87, v23
	v_mul_f32_e32 v22, v22, v160
	v_mul_f32_e32 v22, v86, v22
	v_mul_f32_e32 v21, v21, v160
	v_mul_f32_e32 v21, v85, v21
	v_mul_f32_e32 v20, v20, v160
	v_mul_f32_e32 v20, v84, v20
	v_add_f32_e32 v11, 1.0, v103
	v_fma_f32 v23, v11, v23, v119
	v_add_f32_e32 v10, 1.0, v102
	v_fma_f32 v22, v10, v22, v118
	v_add_f32_e32 v9, 1.0, v101
	v_fma_f32 v21, v9, v21, v117
	v_add_f32_e32 v8, 1.0, v100
	v_fma_f32 v20, v8, v20, v116
	v_cvt_pk_bf16_f32 v16, v16, v17
	v_cvt_pk_bf16_f32 v17, v18, v19
	v_cvt_pk_bf16_f32 v18, v20, v21
	v_cvt_pk_bf16_f32 v19, v22, v23
	global_store_dwordx4 v1, v[16:19], s[4:5]
	v_mul_f32_e32 v27, v27, v160
	v_mul_f32_e32 v27, v91, v27
	v_mul_f32_e32 v26, v26, v160
	v_mul_f32_e32 v26, v90, v26
	v_mul_f32_e32 v25, v25, v160
	v_mul_f32_e32 v25, v89, v25
	v_mul_f32_e32 v24, v24, v160
	v_mul_f32_e32 v24, v88, v24
	v_add_f32_e32 v11, 1.0, v107
	v_fma_f32 v27, v11, v27, v123
	v_add_f32_e32 v10, 1.0, v106
	v_fma_f32 v26, v10, v26, v122
	v_add_f32_e32 v9, 1.0, v105
	v_fma_f32 v25, v9, v25, v121
	v_add_f32_e32 v8, 1.0, v104
	v_fma_f32 v24, v8, v24, v120
	v_mul_f32_e32 v31, v31, v160
	v_mul_f32_e32 v31, v95, v31
	v_mul_f32_e32 v30, v30, v160
	v_mul_f32_e32 v30, v94, v30
	v_mul_f32_e32 v29, v29, v160
	v_mul_f32_e32 v29, v93, v29
	v_mul_f32_e32 v28, v28, v160
	v_mul_f32_e32 v28, v92, v28
	v_add_f32_e32 v11, 1.0, v111
	v_fma_f32 v31, v11, v31, v127
	v_add_f32_e32 v10, 1.0, v110
	v_fma_f32 v30, v10, v30, v126
	v_add_f32_e32 v9, 1.0, v109
	v_fma_f32 v29, v9, v29, v125
	v_add_f32_e32 v8, 1.0, v108
	v_fma_f32 v28, v8, v28, v124
	v_cvt_pk_bf16_f32 v24, v24, v25
	v_cvt_pk_bf16_f32 v25, v26, v27
	v_cvt_pk_bf16_f32 v26, v28, v29
	v_cvt_pk_bf16_f32 v27, v30, v31
	global_store_dwordx4 v1, v[24:27], s[4:5] offset:1024
	s_sub_i32 s7, s10, 0x1000
	s_lshr_b32 s7, s7, 11
	s_add_i32 s7, s7, 1
	s_cmpk_lt_i32 s10, 0x1000
	s_cselect_b32 s7, 0, s7
	s_mulk_i32 s7, 0x6000
	s_add_i32 s7, s7, 0x0
	s_add_u32 s4, s14, s7
	s_addc_u32 s5, s15, 0
	global_load_dwordx4 v[112:115], v0, s[4:5]
	global_load_dwordx4 v[116:119], v0, s[4:5] offset:16
	global_load_dwordx4 v[120:123], v0, s[4:5] offset:2048
	global_load_dwordx4 v[124:127], v0, s[4:5] offset:2064
	s_add_u32 s4, s4, 0x1000
	s_addc_u32 s5, s5, 0
	global_load_dwordx4 v[96:99], v0, s[4:5]
	global_load_dwordx4 v[100:103], v0, s[4:5] offset:16
	global_load_dwordx4 v[104:107], v0, s[4:5] offset:2048
	global_load_dwordx4 v[108:111], v0, s[4:5] offset:2064
	s_waitcnt vmcnt(26)
	s_lshl_b32 s7, s9, 11
	s_add_u32 s4, s46, s7
	s_addc_u32 s5, s47, 0
	s_add_u32 s4, s4, 0x8900000
	s_addc_u32 s5, s5, 0
	v_mul_f32_e32 v35, v35, v161
	v_mul_f32_e32 v35, v83, v35
	v_mul_f32_e32 v34, v34, v161
	v_mul_f32_e32 v34, v82, v34
	v_mul_f32_e32 v33, v33, v161
	v_mul_f32_e32 v33, v81, v33
	v_mul_f32_e32 v32, v32, v161
	v_mul_f32_e32 v32, v80, v32
	v_add_f32_e32 v11, 1.0, v131
	v_fma_f32 v35, v11, v35, v147
	v_add_f32_e32 v10, 1.0, v130
	v_fma_f32 v34, v10, v34, v146
	v_add_f32_e32 v9, 1.0, v129
	v_fma_f32 v33, v9, v33, v145
	v_add_f32_e32 v8, 1.0, v128
	v_fma_f32 v32, v8, v32, v144
	v_mul_f32_e32 v39, v39, v161
	v_mul_f32_e32 v39, v87, v39
	v_mul_f32_e32 v38, v38, v161
	v_mul_f32_e32 v38, v86, v38
	v_mul_f32_e32 v37, v37, v161
	v_mul_f32_e32 v37, v85, v37
	v_mul_f32_e32 v36, v36, v161
	v_mul_f32_e32 v36, v84, v36
	v_add_f32_e32 v11, 1.0, v135
	v_fma_f32 v39, v11, v39, v151
	v_add_f32_e32 v10, 1.0, v134
	v_fma_f32 v38, v10, v38, v150
	v_add_f32_e32 v9, 1.0, v133
	v_fma_f32 v37, v9, v37, v149
	v_add_f32_e32 v8, 1.0, v132
	v_fma_f32 v36, v8, v36, v148
	v_cvt_pk_bf16_f32 v32, v32, v33
	v_cvt_pk_bf16_f32 v33, v34, v35
	v_cvt_pk_bf16_f32 v34, v36, v37
	v_cvt_pk_bf16_f32 v35, v38, v39
	global_store_dwordx4 v1, v[32:35], s[4:5]
	v_mul_f32_e32 v43, v43, v161
	v_mul_f32_e32 v43, v91, v43
	v_mul_f32_e32 v42, v42, v161
	v_mul_f32_e32 v42, v90, v42
	v_mul_f32_e32 v41, v41, v161
	v_mul_f32_e32 v41, v89, v41
	v_mul_f32_e32 v40, v40, v161
	v_mul_f32_e32 v40, v88, v40
	v_add_f32_e32 v11, 1.0, v139
	v_fma_f32 v43, v11, v43, v155
	v_add_f32_e32 v10, 1.0, v138
	v_fma_f32 v42, v10, v42, v154
	v_add_f32_e32 v9, 1.0, v137
	v_fma_f32 v41, v9, v41, v153
	v_add_f32_e32 v8, 1.0, v136
	v_fma_f32 v40, v8, v40, v152
	v_mul_f32_e32 v47, v47, v161
	v_mul_f32_e32 v47, v95, v47
	v_mul_f32_e32 v46, v46, v161
	v_mul_f32_e32 v46, v94, v46
	v_mul_f32_e32 v45, v45, v161
	v_mul_f32_e32 v45, v93, v45
	v_mul_f32_e32 v44, v44, v161
	v_mul_f32_e32 v44, v92, v44
	v_add_f32_e32 v11, 1.0, v143
	v_fma_f32 v47, v11, v47, v159
	v_add_f32_e32 v10, 1.0, v142
	v_fma_f32 v46, v10, v46, v158
	v_add_f32_e32 v9, 1.0, v141
	v_fma_f32 v45, v9, v45, v157
	v_add_f32_e32 v8, 1.0, v140
	v_fma_f32 v44, v8, v44, v156
	v_cvt_pk_bf16_f32 v40, v40, v41
	v_cvt_pk_bf16_f32 v41, v42, v43
	v_cvt_pk_bf16_f32 v42, v44, v45
	v_cvt_pk_bf16_f32 v43, v46, v47
	global_store_dwordx4 v1, v[40:43], s[4:5] offset:1024
	s_sub_i32 s7, s11, 0x1000
	s_lshr_b32 s7, s7, 11
	s_add_i32 s7, s7, 1
	s_cmpk_lt_i32 s11, 0x1000
	s_cselect_b32 s7, 0, s7
	s_mulk_i32 s7, 0x6000
	s_add_i32 s7, s7, 0x0
	s_add_u32 s4, s14, s7
	s_addc_u32 s5, s15, 0
	global_load_dwordx4 v[144:147], v0, s[4:5]
	global_load_dwordx4 v[148:151], v0, s[4:5] offset:16
	global_load_dwordx4 v[152:155], v0, s[4:5] offset:2048
	global_load_dwordx4 v[156:159], v0, s[4:5] offset:2064
	s_add_u32 s4, s4, 0x1000
	s_addc_u32 s5, s5, 0
	global_load_dwordx4 v[128:131], v0, s[4:5]
	global_load_dwordx4 v[132:135], v0, s[4:5] offset:16
	global_load_dwordx4 v[136:139], v0, s[4:5] offset:2048
	global_load_dwordx4 v[140:143], v0, s[4:5] offset:2064
	s_waitcnt vmcnt(10)
	s_lshl_b32 s7, s10, 11
	s_add_u32 s4, s46, s7
	s_addc_u32 s5, s47, 0
	s_add_u32 s4, s4, 0x8900000
	s_addc_u32 s5, s5, 0
	v_mul_f32_e32 v51, v51, v162
	v_mul_f32_e32 v51, v83, v51
	v_mul_f32_e32 v50, v50, v162
	v_mul_f32_e32 v50, v82, v50
	v_mul_f32_e32 v49, v49, v162
	v_mul_f32_e32 v49, v81, v49
	v_mul_f32_e32 v48, v48, v162
	v_mul_f32_e32 v48, v80, v48
	v_add_f32_e32 v11, 1.0, v99
	v_fma_f32 v51, v11, v51, v115
	v_add_f32_e32 v10, 1.0, v98
	v_fma_f32 v50, v10, v50, v114
	v_add_f32_e32 v9, 1.0, v97
	v_fma_f32 v49, v9, v49, v113
	v_add_f32_e32 v8, 1.0, v96
	v_fma_f32 v48, v8, v48, v112
	v_mul_f32_e32 v55, v55, v162
	v_mul_f32_e32 v55, v87, v55
	v_mul_f32_e32 v54, v54, v162
	v_mul_f32_e32 v54, v86, v54
	v_mul_f32_e32 v53, v53, v162
	v_mul_f32_e32 v53, v85, v53
	v_mul_f32_e32 v52, v52, v162
	v_mul_f32_e32 v52, v84, v52
	v_add_f32_e32 v11, 1.0, v103
	v_fma_f32 v55, v11, v55, v119
	v_add_f32_e32 v10, 1.0, v102
	v_fma_f32 v54, v10, v54, v118
	v_add_f32_e32 v9, 1.0, v101
	v_fma_f32 v53, v9, v53, v117
	v_add_f32_e32 v8, 1.0, v100
	v_fma_f32 v52, v8, v52, v116
	v_cvt_pk_bf16_f32 v48, v48, v49
	v_cvt_pk_bf16_f32 v49, v50, v51
	v_cvt_pk_bf16_f32 v50, v52, v53
	v_cvt_pk_bf16_f32 v51, v54, v55
	global_store_dwordx4 v1, v[48:51], s[4:5]
	v_mul_f32_e32 v59, v59, v162
	v_mul_f32_e32 v59, v91, v59
	v_mul_f32_e32 v58, v58, v162
	v_mul_f32_e32 v58, v90, v58
	v_mul_f32_e32 v57, v57, v162
	v_mul_f32_e32 v57, v89, v57
	v_mul_f32_e32 v56, v56, v162
	v_mul_f32_e32 v56, v88, v56
	v_add_f32_e32 v11, 1.0, v107
	v_fma_f32 v59, v11, v59, v123
	v_add_f32_e32 v10, 1.0, v106
	v_fma_f32 v58, v10, v58, v122
	v_add_f32_e32 v9, 1.0, v105
	v_fma_f32 v57, v9, v57, v121
	v_add_f32_e32 v8, 1.0, v104
	v_fma_f32 v56, v8, v56, v120
	v_mul_f32_e32 v63, v63, v162
	v_mul_f32_e32 v63, v95, v63
	v_mul_f32_e32 v62, v62, v162
	v_mul_f32_e32 v62, v94, v62
	v_mul_f32_e32 v61, v61, v162
	v_mul_f32_e32 v61, v93, v61
	v_mul_f32_e32 v60, v60, v162
	v_mul_f32_e32 v60, v92, v60
	v_add_f32_e32 v11, 1.0, v111
	v_fma_f32 v63, v11, v63, v127
	v_add_f32_e32 v10, 1.0, v110
	v_fma_f32 v62, v10, v62, v126
	v_add_f32_e32 v9, 1.0, v109
	v_fma_f32 v61, v9, v61, v125
	v_add_f32_e32 v8, 1.0, v108
	v_fma_f32 v60, v8, v60, v124
	v_cvt_pk_bf16_f32 v56, v56, v57
	v_cvt_pk_bf16_f32 v57, v58, v59
	v_cvt_pk_bf16_f32 v58, v60, v61
	v_cvt_pk_bf16_f32 v59, v62, v63
	global_store_dwordx4 v1, v[56:59], s[4:5] offset:1024
	s_waitcnt vmcnt(2)
	s_lshl_b32 s7, s11, 11
	s_add_u32 s4, s46, s7
	s_addc_u32 s5, s47, 0
	s_add_u32 s4, s4, 0x8900000
	s_addc_u32 s5, s5, 0
	v_mul_f32_e32 v67, v67, v163
	v_mul_f32_e32 v67, v83, v67
	v_mul_f32_e32 v66, v66, v163
	v_mul_f32_e32 v66, v82, v66
	v_mul_f32_e32 v65, v65, v163
	v_mul_f32_e32 v65, v81, v65
	v_mul_f32_e32 v64, v64, v163
	v_mul_f32_e32 v64, v80, v64
	v_add_f32_e32 v11, 1.0, v131
	v_fma_f32 v67, v11, v67, v147
	v_add_f32_e32 v10, 1.0, v130
	v_fma_f32 v66, v10, v66, v146
	v_add_f32_e32 v9, 1.0, v129
	v_fma_f32 v65, v9, v65, v145
	v_add_f32_e32 v8, 1.0, v128
	v_fma_f32 v64, v8, v64, v144
	v_mul_f32_e32 v71, v71, v163
	v_mul_f32_e32 v71, v87, v71
	v_mul_f32_e32 v70, v70, v163
	v_mul_f32_e32 v70, v86, v70
	v_mul_f32_e32 v69, v69, v163
	v_mul_f32_e32 v69, v85, v69
	v_mul_f32_e32 v68, v68, v163
	v_mul_f32_e32 v68, v84, v68
	v_add_f32_e32 v11, 1.0, v135
	v_fma_f32 v71, v11, v71, v151
	v_add_f32_e32 v10, 1.0, v134
	v_fma_f32 v70, v10, v70, v150
	v_add_f32_e32 v9, 1.0, v133
	v_fma_f32 v69, v9, v69, v149
	v_add_f32_e32 v8, 1.0, v132
	v_fma_f32 v68, v8, v68, v148
	v_cvt_pk_bf16_f32 v64, v64, v65
	v_cvt_pk_bf16_f32 v65, v66, v67
	v_cvt_pk_bf16_f32 v66, v68, v69
	v_cvt_pk_bf16_f32 v67, v70, v71
	global_store_dwordx4 v1, v[64:67], s[4:5]
	v_mul_f32_e32 v75, v75, v163
	v_mul_f32_e32 v75, v91, v75
	v_mul_f32_e32 v74, v74, v163
	v_mul_f32_e32 v74, v90, v74
	v_mul_f32_e32 v73, v73, v163
	v_mul_f32_e32 v73, v89, v73
	v_mul_f32_e32 v72, v72, v163
	v_mul_f32_e32 v72, v88, v72
	v_add_f32_e32 v11, 1.0, v139
	v_fma_f32 v75, v11, v75, v155
	v_add_f32_e32 v10, 1.0, v138
	v_fma_f32 v74, v10, v74, v154
	v_add_f32_e32 v9, 1.0, v137
	v_fma_f32 v73, v9, v73, v153
	v_add_f32_e32 v8, 1.0, v136
	v_fma_f32 v72, v8, v72, v152
	v_mul_f32_e32 v79, v79, v163
	v_mul_f32_e32 v79, v95, v79
	v_mul_f32_e32 v78, v78, v163
	v_mul_f32_e32 v78, v94, v78
	v_mul_f32_e32 v77, v77, v163
	v_mul_f32_e32 v77, v93, v77
	v_mul_f32_e32 v76, v76, v163
	v_mul_f32_e32 v76, v92, v76
	v_add_f32_e32 v11, 1.0, v143
	v_fma_f32 v79, v11, v79, v159
	v_add_f32_e32 v10, 1.0, v142
	v_fma_f32 v78, v10, v78, v158
	v_add_f32_e32 v9, 1.0, v141
	v_fma_f32 v77, v9, v77, v157
	v_add_f32_e32 v8, 1.0, v140
	v_fma_f32 v76, v8, v76, v156
	v_cvt_pk_bf16_f32 v72, v72, v73
	v_cvt_pk_bf16_f32 v73, v74, v75
	v_cvt_pk_bf16_f32 v74, v76, v77
	v_cvt_pk_bf16_f32 v75, v78, v79
	global_store_dwordx4 v1, v[72:75], s[4:5] offset:1024
	s_lshl_b32 s7, s6, 2
	s_add_i32 s3, s3, s7
	s_cmpk_lt_i32 s3, 0x2000
	s_cbranch_scc1 .Lnorm1f_loop

.Lnorm1_regular:
	v_and_b32_e32 v8, 63, v211
	v_lshlrev_b32_e32 v0, 5, v8
	v_lshlrev_b32_e32 v1, 4, v8
	v_lshlrev_b32_e32 v9, 2, v8
	v_xor_b32_e32 v2, 0x4, v9
	v_xor_b32_e32 v3, 0x8, v9
	v_xor_b32_e32 v4, 0x10, v9
	v_xor_b32_e32 v5, 0x20, v9
	v_xor_b32_e32 v6, 0x40, v9
	v_xor_b32_e32 v7, 0x80, v9
	v_readlane_b32 s3, v240, 55
	v_readlane_b32 s6, v239, 10
	s_lshr_b32 s3, s3, 6
	s_lshl_b32 s7, s78, 3
	s_add_i32 s3, s3, s7
	s_lshl_b32 s6, s6, 3
	s_cmpk_lt_i32 s3, 0x2000
	s_cbranch_scc0 .Lnorm1_end
.Lnorm1_loop:
	s_mov_b32 s8, s3
	s_add_i32 s9, s8, s6
	s_add_i32 s10, s9, s6
	s_add_i32 s11, s10, s6
	s_cmpk_lt_i32 s9, 0x2000
	s_cselect_b32 s9, s9, s3
	s_cmpk_lt_i32 s10, 0x2000
	s_cselect_b32 s10, s10, s3
	s_cmpk_lt_i32 s11, 0x2000
	s_cselect_b32 s11, s11, s3
	s_lshl_b32 s7, s8, 12
	s_add_u32 s4, s46, s7
	s_addc_u32 s5, s47, 0
	s_add_u32 s4, s4, 0x6900000
	s_addc_u32 s5, s5, 0
	global_load_dwordx4 v[16:19], v0, s[4:5]
	global_load_dwordx4 v[20:23], v0, s[4:5] offset:16
	global_load_dwordx4 v[24:27], v0, s[4:5] offset:2048
	global_load_dwordx4 v[28:31], v0, s[4:5] offset:2064
	s_lshl_b32 s7, s9, 12
	s_add_u32 s4, s46, s7
	s_addc_u32 s5, s47, 0
	s_add_u32 s4, s4, 0x6900000
	s_addc_u32 s5, s5, 0
	global_load_dwordx4 v[32:35], v0, s[4:5]
	global_load_dwordx4 v[36:39], v0, s[4:5] offset:16
	global_load_dwordx4 v[40:43], v0, s[4:5] offset:2048
	global_load_dwordx4 v[44:47], v0, s[4:5] offset:2064
	s_lshl_b32 s7, s10, 12
	s_add_u32 s4, s46, s7
	s_addc_u32 s5, s47, 0
	s_add_u32 s4, s4, 0x6900000
	s_addc_u32 s5, s5, 0
	global_load_dwordx4 v[48:51], v0, s[4:5]
	global_load_dwordx4 v[52:55], v0, s[4:5] offset:16
	global_load_dwordx4 v[56:59], v0, s[4:5] offset:2048
	global_load_dwordx4 v[60:63], v0, s[4:5] offset:2064
	s_lshl_b32 s7, s11, 12
	s_add_u32 s4, s46, s7
	s_addc_u32 s5, s47, 0
	s_add_u32 s4, s4, 0x6900000
	s_addc_u32 s5, s5, 0
	global_load_dwordx4 v[64:67], v0, s[4:5]
	global_load_dwordx4 v[68:71], v0, s[4:5] offset:16
	global_load_dwordx4 v[72:75], v0, s[4:5] offset:2048
	global_load_dwordx4 v[76:79], v0, s[4:5] offset:2064
	global_load_dwordx4 v[80:83], v0, s[16:17]
	global_load_dwordx4 v[84:87], v0, s[16:17] offset:16
	global_load_dwordx4 v[88:91], v0, s[16:17] offset:2048
	global_load_dwordx4 v[92:95], v0, s[16:17] offset:2064
	s_sub_i32 s7, s8, 0x1000
	s_lshr_b32 s7, s7, 11
	s_add_i32 s7, s7, 1
	s_cmpk_lt_i32 s8, 0x1000
	s_cselect_b32 s7, 0, s7
	s_mulk_i32 s7, 0x6000
	s_add_i32 s7, s7, 0x0
	s_add_u32 s4, s14, s7
	s_addc_u32 s5, s15, 0
	global_load_dwordx4 v[112:115], v0, s[4:5]
	global_load_dwordx4 v[116:119], v0, s[4:5] offset:16
	global_load_dwordx4 v[120:123], v0, s[4:5] offset:2048
	global_load_dwordx4 v[124:127], v0, s[4:5] offset:2064
	s_add_u32 s4, s4, 0x1000
	s_addc_u32 s5, s5, 0
	global_load_dwordx4 v[96:99], v0, s[4:5]
	global_load_dwordx4 v[100:103], v0, s[4:5] offset:16
	global_load_dwordx4 v[104:107], v0, s[4:5] offset:2048
	global_load_dwordx4 v[108:111], v0, s[4:5] offset:2064
	s_sub_i32 s7, s9, 0x1000
	s_lshr_b32 s7, s7, 11
	s_add_i32 s7, s7, 1
	s_cmpk_lt_i32 s9, 0x1000
	s_cselect_b32 s7, 0, s7
	s_mulk_i32 s7, 0x6000
	s_add_i32 s7, s7, 0x0
	s_add_u32 s4, s14, s7
	s_addc_u32 s5, s15, 0
	global_load_dwordx4 v[144:147], v0, s[4:5]
	global_load_dwordx4 v[148:151], v0, s[4:5] offset:16
	global_load_dwordx4 v[152:155], v0, s[4:5] offset:2048
	global_load_dwordx4 v[156:159], v0, s[4:5] offset:2064
	s_add_u32 s4, s4, 0x1000
	s_addc_u32 s5, s5, 0
	global_load_dwordx4 v[128:131], v0, s[4:5]
	global_load_dwordx4 v[132:135], v0, s[4:5] offset:16
	global_load_dwordx4 v[136:139], v0, s[4:5] offset:2048
	global_load_dwordx4 v[140:143], v0, s[4:5] offset:2064
	s_waitcnt vmcnt(32)
	v_mul_f32_e32 v160, v17, v17
	v_mul_f32_e32 v9, v19, v19
	v_fmac_f32_e32 v160, v16, v16
	v_fmac_f32_e32 v9, v18, v18
	v_add_f32_e32 v160, v160, v9
	v_mul_f32_e32 v8, v21, v21
	v_mul_f32_e32 v9, v23, v23
	v_fmac_f32_e32 v8, v20, v20
	v_fmac_f32_e32 v9, v22, v22
	v_add_f32_e32 v8, v8, v9
	v_add_f32_e32 v160, v160, v8
	v_mul_f32_e32 v8, v25, v25
	v_mul_f32_e32 v9, v27, v27
	v_fmac_f32_e32 v8, v24, v24
	v_fmac_f32_e32 v9, v26, v26
	v_add_f32_e32 v8, v8, v9
	v_add_f32_e32 v160, v160, v8
	v_mul_f32_e32 v8, v29, v29
	v_mul_f32_e32 v9, v31, v31
	v_fmac_f32_e32 v8, v28, v28
	v_fmac_f32_e32 v9, v30, v30
	v_add_f32_e32 v8, v8, v9
	v_add_f32_e32 v160, v160, v8
	s_waitcnt vmcnt(28)
	v_mul_f32_e32 v161, v33, v33
	v_mul_f32_e32 v9, v35, v35
	v_fmac_f32_e32 v161, v32, v32
	v_fmac_f32_e32 v9, v34, v34
	v_add_f32_e32 v161, v161, v9
	v_mul_f32_e32 v8, v37, v37
	v_mul_f32_e32 v9, v39, v39
	v_fmac_f32_e32 v8, v36, v36
	v_fmac_f32_e32 v9, v38, v38
	v_add_f32_e32 v8, v8, v9
	v_add_f32_e32 v161, v161, v8
	v_mul_f32_e32 v8, v41, v41
	v_mul_f32_e32 v9, v43, v43
	v_fmac_f32_e32 v8, v40, v40
	v_fmac_f32_e32 v9, v42, v42
	v_add_f32_e32 v8, v8, v9
	v_add_f32_e32 v161, v161, v8
	v_mul_f32_e32 v8, v45, v45
	v_mul_f32_e32 v9, v47, v47
	v_fmac_f32_e32 v8, v44, v44
	v_fmac_f32_e32 v9, v46, v46
	v_add_f32_e32 v8, v8, v9
	v_add_f32_e32 v161, v161, v8
	s_waitcnt vmcnt(24)
	v_mul_f32_e32 v162, v49, v49
	v_mul_f32_e32 v9, v51, v51
	v_fmac_f32_e32 v162, v48, v48
	v_fmac_f32_e32 v9, v50, v50
	v_add_f32_e32 v162, v162, v9
	v_mul_f32_e32 v8, v53, v53
	v_mul_f32_e32 v9, v55, v55
	v_fmac_f32_e32 v8, v52, v52
	v_fmac_f32_e32 v9, v54, v54
	v_add_f32_e32 v8, v8, v9
	v_add_f32_e32 v162, v162, v8
	v_mul_f32_e32 v8, v57, v57
	v_mul_f32_e32 v9, v59, v59
	v_fmac_f32_e32 v8, v56, v56
	v_fmac_f32_e32 v9, v58, v58
	v_add_f32_e32 v8, v8, v9
	v_add_f32_e32 v162, v162, v8
	v_mul_f32_e32 v8, v61, v61
	v_mul_f32_e32 v9, v63, v63
	v_fmac_f32_e32 v8, v60, v60
	v_fmac_f32_e32 v9, v62, v62
	v_add_f32_e32 v8, v8, v9
	v_add_f32_e32 v162, v162, v8
	s_waitcnt vmcnt(20)
	v_mul_f32_e32 v163, v65, v65
	v_mul_f32_e32 v9, v67, v67
	v_fmac_f32_e32 v163, v64, v64
	v_fmac_f32_e32 v9, v66, v66
	v_add_f32_e32 v163, v163, v9
	v_mul_f32_e32 v8, v69, v69
	v_mul_f32_e32 v9, v71, v71
	v_fmac_f32_e32 v8, v68, v68
	v_fmac_f32_e32 v9, v70, v70
	v_add_f32_e32 v8, v8, v9
	v_add_f32_e32 v163, v163, v8
	v_mul_f32_e32 v8, v73, v73
	v_mul_f32_e32 v9, v75, v75
	v_fmac_f32_e32 v8, v72, v72
	v_fmac_f32_e32 v9, v74, v74
	v_add_f32_e32 v8, v8, v9
	v_add_f32_e32 v163, v163, v8
	v_mul_f32_e32 v8, v77, v77
	v_mul_f32_e32 v9, v79, v79
	v_fmac_f32_e32 v8, v76, v76
	v_fmac_f32_e32 v9, v78, v78
	v_add_f32_e32 v8, v8, v9
	v_add_f32_e32 v163, v163, v8
	ds_bpermute_b32 v8, v2, v160
	ds_bpermute_b32 v9, v2, v161
	ds_bpermute_b32 v10, v2, v162
	ds_bpermute_b32 v11, v2, v163
	s_waitcnt lgkmcnt(3)
	v_add_f32_e32 v160, v160, v8
	s_waitcnt lgkmcnt(2)
	v_add_f32_e32 v161, v161, v9
	s_waitcnt lgkmcnt(1)
	v_add_f32_e32 v162, v162, v10
	s_waitcnt lgkmcnt(0)
	v_add_f32_e32 v163, v163, v11
	ds_bpermute_b32 v8, v3, v160
	ds_bpermute_b32 v9, v3, v161
	ds_bpermute_b32 v10, v3, v162
	ds_bpermute_b32 v11, v3, v163
	s_waitcnt lgkmcnt(3)
	v_add_f32_e32 v160, v160, v8
	s_waitcnt lgkmcnt(2)
	v_add_f32_e32 v161, v161, v9
	s_waitcnt lgkmcnt(1)
	v_add_f32_e32 v162, v162, v10
	s_waitcnt lgkmcnt(0)
	v_add_f32_e32 v163, v163, v11
	ds_bpermute_b32 v8, v4, v160
	ds_bpermute_b32 v9, v4, v161
	ds_bpermute_b32 v10, v4, v162
	ds_bpermute_b32 v11, v4, v163
	s_waitcnt lgkmcnt(3)
	v_add_f32_e32 v160, v160, v8
	s_waitcnt lgkmcnt(2)
	v_add_f32_e32 v161, v161, v9
	s_waitcnt lgkmcnt(1)
	v_add_f32_e32 v162, v162, v10
	s_waitcnt lgkmcnt(0)
	v_add_f32_e32 v163, v163, v11
	ds_bpermute_b32 v8, v5, v160
	ds_bpermute_b32 v9, v5, v161
	ds_bpermute_b32 v10, v5, v162
	ds_bpermute_b32 v11, v5, v163
	s_waitcnt lgkmcnt(3)
	v_add_f32_e32 v160, v160, v8
	s_waitcnt lgkmcnt(2)
	v_add_f32_e32 v161, v161, v9
	s_waitcnt lgkmcnt(1)
	v_add_f32_e32 v162, v162, v10
	s_waitcnt lgkmcnt(0)
	v_add_f32_e32 v163, v163, v11
	ds_bpermute_b32 v8, v6, v160
	ds_bpermute_b32 v9, v6, v161
	ds_bpermute_b32 v10, v6, v162
	ds_bpermute_b32 v11, v6, v163
	s_waitcnt lgkmcnt(3)
	v_add_f32_e32 v160, v160, v8
	s_waitcnt lgkmcnt(2)
	v_add_f32_e32 v161, v161, v9
	s_waitcnt lgkmcnt(1)
	v_add_f32_e32 v162, v162, v10
	s_waitcnt lgkmcnt(0)
	v_add_f32_e32 v163, v163, v11
	ds_bpermute_b32 v8, v7, v160
	ds_bpermute_b32 v9, v7, v161
	ds_bpermute_b32 v10, v7, v162
	ds_bpermute_b32 v11, v7, v163
	s_waitcnt lgkmcnt(3)
	v_add_f32_e32 v160, v160, v8
	s_waitcnt lgkmcnt(2)
	v_add_f32_e32 v161, v161, v9
	s_waitcnt lgkmcnt(1)
	v_add_f32_e32 v162, v162, v10
	s_waitcnt lgkmcnt(0)
	v_add_f32_e32 v163, v163, v11
	s_mov_b32 s7, 0xf800000
	v_fmamk_f32 v160, v160, 0x3a800000, v190
	v_mul_f32_e32 v8, 0x4f800000, v160
	v_cmp_gt_f32_e32 vcc, s7, v160
	s_nop 1
	v_cndmask_b32_e32 v160, v160, v8, vcc
	v_sqrt_f32_e32 v8, v160
	s_nop 0
	v_add_u32_e32 v9, -1, v8
	v_fma_f32 v10, -v9, v8, v160
	v_cmp_ge_f32_e64 s[4:5], 0, v10
	v_add_u32_e32 v10, 1, v8
	s_nop 0
	v_cndmask_b32_e64 v9, v8, v9, s[4:5]
	v_fma_f32 v8, -v10, v8, v160
	v_cmp_lt_f32_e64 s[4:5], 0, v8
	s_nop 1
	v_cndmask_b32_e64 v8, v9, v10, s[4:5]
	v_mul_f32_e32 v9, 0x37800000, v8
	v_cndmask_b32_e32 v8, v8, v9, vcc
	v_cmp_class_f32_e32 vcc, v160, v191
	s_nop 1
	v_cndmask_b32_e32 v160, v8, v160, vcc
	v_div_scale_f32 v8, s[4:5], v160, v160, 1.0
	v_rcp_f32_e32 v9, v8
	s_nop 0
	v_fma_f32 v10, -v8, v9, 1.0
	v_fmac_f32_e32 v9, v10, v9
	v_div_scale_f32 v10, vcc, 1.0, v160, 1.0
	v_mul_f32_e32 v11, v10, v9
	v_fma_f32 v12, -v8, v11, v10
	v_fmac_f32_e32 v11, v12, v9
	v_fma_f32 v8, -v8, v11, v10
	v_div_fmas_f32 v8, v8, v9, v11
	v_div_fixup_f32 v160, v8, v160, 1.0
	s_mov_b32 s7, 0xf800000
	v_fmamk_f32 v161, v161, 0x3a800000, v190
	v_mul_f32_e32 v8, 0x4f800000, v161
	v_cmp_gt_f32_e32 vcc, s7, v161
	s_nop 1
	v_cndmask_b32_e32 v161, v161, v8, vcc
	v_sqrt_f32_e32 v8, v161
	s_nop 0
	v_add_u32_e32 v9, -1, v8
	v_fma_f32 v10, -v9, v8, v161
	v_cmp_ge_f32_e64 s[4:5], 0, v10
	v_add_u32_e32 v10, 1, v8
	s_nop 0
	v_cndmask_b32_e64 v9, v8, v9, s[4:5]
	v_fma_f32 v8, -v10, v8, v161
	v_cmp_lt_f32_e64 s[4:5], 0, v8
	s_nop 1
	v_cndmask_b32_e64 v8, v9, v10, s[4:5]
	v_mul_f32_e32 v9, 0x37800000, v8
	v_cndmask_b32_e32 v8, v8, v9, vcc
	v_cmp_class_f32_e32 vcc, v161, v191
	s_nop 1
	v_cndmask_b32_e32 v161, v8, v161, vcc
	v_div_scale_f32 v8, s[4:5], v161, v161, 1.0
	v_rcp_f32_e32 v9, v8
	s_nop 0
	v_fma_f32 v10, -v8, v9, 1.0
	v_fmac_f32_e32 v9, v10, v9
	v_div_scale_f32 v10, vcc, 1.0, v161, 1.0
	v_mul_f32_e32 v11, v10, v9
	v_fma_f32 v12, -v8, v11, v10
	v_fmac_f32_e32 v11, v12, v9
	v_fma_f32 v8, -v8, v11, v10
	v_div_fmas_f32 v8, v8, v9, v11
	v_div_fixup_f32 v161, v8, v161, 1.0
	s_mov_b32 s7, 0xf800000
	v_fmamk_f32 v162, v162, 0x3a800000, v190
	v_mul_f32_e32 v8, 0x4f800000, v162
	v_cmp_gt_f32_e32 vcc, s7, v162
	s_nop 1
	v_cndmask_b32_e32 v162, v162, v8, vcc
	v_sqrt_f32_e32 v8, v162
	s_nop 0
	v_add_u32_e32 v9, -1, v8
	v_fma_f32 v10, -v9, v8, v162
	v_cmp_ge_f32_e64 s[4:5], 0, v10
	v_add_u32_e32 v10, 1, v8
	s_nop 0
	v_cndmask_b32_e64 v9, v8, v9, s[4:5]
	v_fma_f32 v8, -v10, v8, v162
	v_cmp_lt_f32_e64 s[4:5], 0, v8
	s_nop 1
	v_cndmask_b32_e64 v8, v9, v10, s[4:5]
	v_mul_f32_e32 v9, 0x37800000, v8
	v_cndmask_b32_e32 v8, v8, v9, vcc
	v_cmp_class_f32_e32 vcc, v162, v191
	s_nop 1
	v_cndmask_b32_e32 v162, v8, v162, vcc
	v_div_scale_f32 v8, s[4:5], v162, v162, 1.0
	v_rcp_f32_e32 v9, v8
	s_nop 0
	v_fma_f32 v10, -v8, v9, 1.0
	v_fmac_f32_e32 v9, v10, v9
	v_div_scale_f32 v10, vcc, 1.0, v162, 1.0
	v_mul_f32_e32 v11, v10, v9
	v_fma_f32 v12, -v8, v11, v10
	v_fmac_f32_e32 v11, v12, v9
	v_fma_f32 v8, -v8, v11, v10
	v_div_fmas_f32 v8, v8, v9, v11
	v_div_fixup_f32 v162, v8, v162, 1.0
	s_mov_b32 s7, 0xf800000
	v_fmamk_f32 v163, v163, 0x3a800000, v190
	v_mul_f32_e32 v8, 0x4f800000, v163
	v_cmp_gt_f32_e32 vcc, s7, v163
	s_nop 1
	v_cndmask_b32_e32 v163, v163, v8, vcc
	v_sqrt_f32_e32 v8, v163
	s_nop 0
	v_add_u32_e32 v9, -1, v8
	v_fma_f32 v10, -v9, v8, v163
	v_cmp_ge_f32_e64 s[4:5], 0, v10
	v_add_u32_e32 v10, 1, v8
	s_nop 0
	v_cndmask_b32_e64 v9, v8, v9, s[4:5]
	v_fma_f32 v8, -v10, v8, v163
	v_cmp_lt_f32_e64 s[4:5], 0, v8
	s_nop 1
	v_cndmask_b32_e64 v8, v9, v10, s[4:5]
	v_mul_f32_e32 v9, 0x37800000, v8
	v_cndmask_b32_e32 v8, v8, v9, vcc
	v_cmp_class_f32_e32 vcc, v163, v191
	s_nop 1
	v_cndmask_b32_e32 v163, v8, v163, vcc
	v_div_scale_f32 v8, s[4:5], v163, v163, 1.0
	v_rcp_f32_e32 v9, v8
	s_nop 0
	v_fma_f32 v10, -v8, v9, 1.0
	v_fmac_f32_e32 v9, v10, v9
	v_div_scale_f32 v10, vcc, 1.0, v163, 1.0
	v_mul_f32_e32 v11, v10, v9
	v_fma_f32 v12, -v8, v11, v10
	v_fmac_f32_e32 v11, v12, v9
	v_fma_f32 v8, -v8, v11, v10
	v_div_fmas_f32 v8, v8, v9, v11
	v_div_fixup_f32 v163, v8, v163, 1.0
	s_waitcnt vmcnt(8)
	s_lshl_b32 s7, s8, 11
	s_add_u32 s4, s46, s7
	s_addc_u32 s5, s47, 0
	s_add_u32 s4, s4, 0x8900000
	s_addc_u32 s5, s5, 0
	v_mul_f32_e32 v19, v19, v160
	v_mul_f32_e32 v19, v83, v19
	v_mul_f32_e32 v18, v18, v160
	v_mul_f32_e32 v18, v82, v18
	v_mul_f32_e32 v17, v17, v160
	v_mul_f32_e32 v17, v81, v17
	v_mul_f32_e32 v16, v16, v160
	v_mul_f32_e32 v16, v80, v16
	v_add_f32_e32 v11, 1.0, v99
	v_fma_f32 v19, v11, v19, v115
	v_add_f32_e32 v10, 1.0, v98
	v_fma_f32 v18, v10, v18, v114
	v_add_f32_e32 v9, 1.0, v97
	v_fma_f32 v17, v9, v17, v113
	v_add_f32_e32 v8, 1.0, v96
	v_fma_f32 v16, v8, v16, v112
	v_mul_f32_e32 v23, v23, v160
	v_mul_f32_e32 v23, v87, v23
	v_mul_f32_e32 v22, v22, v160
	v_mul_f32_e32 v22, v86, v22
	v_mul_f32_e32 v21, v21, v160
	v_mul_f32_e32 v21, v85, v21
	v_mul_f32_e32 v20, v20, v160
	v_mul_f32_e32 v20, v84, v20
	v_add_f32_e32 v11, 1.0, v103
	v_fma_f32 v23, v11, v23, v119
	v_add_f32_e32 v10, 1.0, v102
	v_fma_f32 v22, v10, v22, v118
	v_add_f32_e32 v9, 1.0, v101
	v_fma_f32 v21, v9, v21, v117
	v_add_f32_e32 v8, 1.0, v100
	v_fma_f32 v20, v8, v20, v116
	v_cvt_pk_bf16_f32 v16, v16, v17
	v_cvt_pk_bf16_f32 v17, v18, v19
	v_cvt_pk_bf16_f32 v18, v20, v21
	v_cvt_pk_bf16_f32 v19, v22, v23
	global_store_dwordx4 v1, v[16:19], s[4:5]
	v_mul_f32_e32 v27, v27, v160
	v_mul_f32_e32 v27, v91, v27
	v_mul_f32_e32 v26, v26, v160
	v_mul_f32_e32 v26, v90, v26
	v_mul_f32_e32 v25, v25, v160
	v_mul_f32_e32 v25, v89, v25
	v_mul_f32_e32 v24, v24, v160
	v_mul_f32_e32 v24, v88, v24
	v_add_f32_e32 v11, 1.0, v107
	v_fma_f32 v27, v11, v27, v123
	v_add_f32_e32 v10, 1.0, v106
	v_fma_f32 v26, v10, v26, v122
	v_add_f32_e32 v9, 1.0, v105
	v_fma_f32 v25, v9, v25, v121
	v_add_f32_e32 v8, 1.0, v104
	v_fma_f32 v24, v8, v24, v120
	v_mul_f32_e32 v31, v31, v160
	v_mul_f32_e32 v31, v95, v31
	v_mul_f32_e32 v30, v30, v160
	v_mul_f32_e32 v30, v94, v30
	v_mul_f32_e32 v29, v29, v160
	v_mul_f32_e32 v29, v93, v29
	v_mul_f32_e32 v28, v28, v160
	v_mul_f32_e32 v28, v92, v28
	v_add_f32_e32 v11, 1.0, v111
	v_fma_f32 v31, v11, v31, v127
	v_add_f32_e32 v10, 1.0, v110
	v_fma_f32 v30, v10, v30, v126
	v_add_f32_e32 v9, 1.0, v109
	v_fma_f32 v29, v9, v29, v125
	v_add_f32_e32 v8, 1.0, v108
	v_fma_f32 v28, v8, v28, v124
	v_cvt_pk_bf16_f32 v24, v24, v25
	v_cvt_pk_bf16_f32 v25, v26, v27
	v_cvt_pk_bf16_f32 v26, v28, v29
	v_cvt_pk_bf16_f32 v27, v30, v31
	global_store_dwordx4 v1, v[24:27], s[4:5] offset:1024
	s_sub_i32 s7, s10, 0x1000
	s_lshr_b32 s7, s7, 11
	s_add_i32 s7, s7, 1
	s_cmpk_lt_i32 s10, 0x1000
	s_cselect_b32 s7, 0, s7
	s_mulk_i32 s7, 0x6000
	s_add_i32 s7, s7, 0x0
	s_add_u32 s4, s14, s7
	s_addc_u32 s5, s15, 0
	global_load_dwordx4 v[112:115], v0, s[4:5]
	global_load_dwordx4 v[116:119], v0, s[4:5] offset:16
	global_load_dwordx4 v[120:123], v0, s[4:5] offset:2048
	global_load_dwordx4 v[124:127], v0, s[4:5] offset:2064
	s_add_u32 s4, s4, 0x1000
	s_addc_u32 s5, s5, 0
	global_load_dwordx4 v[96:99], v0, s[4:5]
	global_load_dwordx4 v[100:103], v0, s[4:5] offset:16
	global_load_dwordx4 v[104:107], v0, s[4:5] offset:2048
	global_load_dwordx4 v[108:111], v0, s[4:5] offset:2064
	s_waitcnt vmcnt(10)
	s_lshl_b32 s7, s9, 11
	s_add_u32 s4, s46, s7
	s_addc_u32 s5, s47, 0
	s_add_u32 s4, s4, 0x8900000
	s_addc_u32 s5, s5, 0
	v_mul_f32_e32 v35, v35, v161
	v_mul_f32_e32 v35, v83, v35
	v_mul_f32_e32 v34, v34, v161
	v_mul_f32_e32 v34, v82, v34
	v_mul_f32_e32 v33, v33, v161
	v_mul_f32_e32 v33, v81, v33
	v_mul_f32_e32 v32, v32, v161
	v_mul_f32_e32 v32, v80, v32
	v_add_f32_e32 v11, 1.0, v131
	v_fma_f32 v35, v11, v35, v147
	v_add_f32_e32 v10, 1.0, v130
	v_fma_f32 v34, v10, v34, v146
	v_add_f32_e32 v9, 1.0, v129
	v_fma_f32 v33, v9, v33, v145
	v_add_f32_e32 v8, 1.0, v128
	v_fma_f32 v32, v8, v32, v144
	v_mul_f32_e32 v39, v39, v161
	v_mul_f32_e32 v39, v87, v39
	v_mul_f32_e32 v38, v38, v161
	v_mul_f32_e32 v38, v86, v38
	v_mul_f32_e32 v37, v37, v161
	v_mul_f32_e32 v37, v85, v37
	v_mul_f32_e32 v36, v36, v161
	v_mul_f32_e32 v36, v84, v36
	v_add_f32_e32 v11, 1.0, v135
	v_fma_f32 v39, v11, v39, v151
	v_add_f32_e32 v10, 1.0, v134
	v_fma_f32 v38, v10, v38, v150
	v_add_f32_e32 v9, 1.0, v133
	v_fma_f32 v37, v9, v37, v149
	v_add_f32_e32 v8, 1.0, v132
	v_fma_f32 v36, v8, v36, v148
	v_cvt_pk_bf16_f32 v32, v32, v33
	v_cvt_pk_bf16_f32 v33, v34, v35
	v_cvt_pk_bf16_f32 v34, v36, v37
	v_cvt_pk_bf16_f32 v35, v38, v39
	global_store_dwordx4 v1, v[32:35], s[4:5]
	v_mul_f32_e32 v43, v43, v161
	v_mul_f32_e32 v43, v91, v43
	v_mul_f32_e32 v42, v42, v161
	v_mul_f32_e32 v42, v90, v42
	v_mul_f32_e32 v41, v41, v161
	v_mul_f32_e32 v41, v89, v41
	v_mul_f32_e32 v40, v40, v161
	v_mul_f32_e32 v40, v88, v40
	v_add_f32_e32 v11, 1.0, v139
	v_fma_f32 v43, v11, v43, v155
	v_add_f32_e32 v10, 1.0, v138
	v_fma_f32 v42, v10, v42, v154
	v_add_f32_e32 v9, 1.0, v137
	v_fma_f32 v41, v9, v41, v153
	v_add_f32_e32 v8, 1.0, v136
	v_fma_f32 v40, v8, v40, v152
	v_mul_f32_e32 v47, v47, v161
	v_mul_f32_e32 v47, v95, v47
	v_mul_f32_e32 v46, v46, v161
	v_mul_f32_e32 v46, v94, v46
	v_mul_f32_e32 v45, v45, v161
	v_mul_f32_e32 v45, v93, v45
	v_mul_f32_e32 v44, v44, v161
	v_mul_f32_e32 v44, v92, v44
	v_add_f32_e32 v11, 1.0, v143
	v_fma_f32 v47, v11, v47, v159
	v_add_f32_e32 v10, 1.0, v142
	v_fma_f32 v46, v10, v46, v158
	v_add_f32_e32 v9, 1.0, v141
	v_fma_f32 v45, v9, v45, v157
	v_add_f32_e32 v8, 1.0, v140
	v_fma_f32 v44, v8, v44, v156
	v_cvt_pk_bf16_f32 v40, v40, v41
	v_cvt_pk_bf16_f32 v41, v42, v43
	v_cvt_pk_bf16_f32 v42, v44, v45
	v_cvt_pk_bf16_f32 v43, v46, v47
	global_store_dwordx4 v1, v[40:43], s[4:5] offset:1024
	s_sub_i32 s7, s11, 0x1000
	s_lshr_b32 s7, s7, 11
	s_add_i32 s7, s7, 1
	s_cmpk_lt_i32 s11, 0x1000
	s_cselect_b32 s7, 0, s7
	s_mulk_i32 s7, 0x6000
	s_add_i32 s7, s7, 0x0
	s_add_u32 s4, s14, s7
	s_addc_u32 s5, s15, 0
	global_load_dwordx4 v[144:147], v0, s[4:5]
	global_load_dwordx4 v[148:151], v0, s[4:5] offset:16
	global_load_dwordx4 v[152:155], v0, s[4:5] offset:2048
	global_load_dwordx4 v[156:159], v0, s[4:5] offset:2064
	s_add_u32 s4, s4, 0x1000
	s_addc_u32 s5, s5, 0
	global_load_dwordx4 v[128:131], v0, s[4:5]
	global_load_dwordx4 v[132:135], v0, s[4:5] offset:16
	global_load_dwordx4 v[136:139], v0, s[4:5] offset:2048
	global_load_dwordx4 v[140:143], v0, s[4:5] offset:2064
	s_waitcnt vmcnt(10)
	s_lshl_b32 s7, s10, 11
	s_add_u32 s4, s46, s7
	s_addc_u32 s5, s47, 0
	s_add_u32 s4, s4, 0x8900000
	s_addc_u32 s5, s5, 0
	v_mul_f32_e32 v51, v51, v162
	v_mul_f32_e32 v51, v83, v51
	v_mul_f32_e32 v50, v50, v162
	v_mul_f32_e32 v50, v82, v50
	v_mul_f32_e32 v49, v49, v162
	v_mul_f32_e32 v49, v81, v49
	v_mul_f32_e32 v48, v48, v162
	v_mul_f32_e32 v48, v80, v48
	v_add_f32_e32 v11, 1.0, v99
	v_fma_f32 v51, v11, v51, v115
	v_add_f32_e32 v10, 1.0, v98
	v_fma_f32 v50, v10, v50, v114
	v_add_f32_e32 v9, 1.0, v97
	v_fma_f32 v49, v9, v49, v113
	v_add_f32_e32 v8, 1.0, v96
	v_fma_f32 v48, v8, v48, v112
	v_mul_f32_e32 v55, v55, v162
	v_mul_f32_e32 v55, v87, v55
	v_mul_f32_e32 v54, v54, v162
	v_mul_f32_e32 v54, v86, v54
	v_mul_f32_e32 v53, v53, v162
	v_mul_f32_e32 v53, v85, v53
	v_mul_f32_e32 v52, v52, v162
	v_mul_f32_e32 v52, v84, v52
	v_add_f32_e32 v11, 1.0, v103
	v_fma_f32 v55, v11, v55, v119
	v_add_f32_e32 v10, 1.0, v102
	v_fma_f32 v54, v10, v54, v118
	v_add_f32_e32 v9, 1.0, v101
	v_fma_f32 v53, v9, v53, v117
	v_add_f32_e32 v8, 1.0, v100
	v_fma_f32 v52, v8, v52, v116
	v_cvt_pk_bf16_f32 v48, v48, v49
	v_cvt_pk_bf16_f32 v49, v50, v51
	v_cvt_pk_bf16_f32 v50, v52, v53
	v_cvt_pk_bf16_f32 v51, v54, v55
	global_store_dwordx4 v1, v[48:51], s[4:5]
	v_mul_f32_e32 v59, v59, v162
	v_mul_f32_e32 v59, v91, v59
	v_mul_f32_e32 v58, v58, v162
	v_mul_f32_e32 v58, v90, v58
	v_mul_f32_e32 v57, v57, v162
	v_mul_f32_e32 v57, v89, v57
	v_mul_f32_e32 v56, v56, v162
	v_mul_f32_e32 v56, v88, v56
	v_add_f32_e32 v11, 1.0, v107
	v_fma_f32 v59, v11, v59, v123
	v_add_f32_e32 v10, 1.0, v106
	v_fma_f32 v58, v10, v58, v122
	v_add_f32_e32 v9, 1.0, v105
	v_fma_f32 v57, v9, v57, v121
	v_add_f32_e32 v8, 1.0, v104
	v_fma_f32 v56, v8, v56, v120
	v_mul_f32_e32 v63, v63, v162
	v_mul_f32_e32 v63, v95, v63
	v_mul_f32_e32 v62, v62, v162
	v_mul_f32_e32 v62, v94, v62
	v_mul_f32_e32 v61, v61, v162
	v_mul_f32_e32 v61, v93, v61
	v_mul_f32_e32 v60, v60, v162
	v_mul_f32_e32 v60, v92, v60
	v_add_f32_e32 v11, 1.0, v111
	v_fma_f32 v63, v11, v63, v127
	v_add_f32_e32 v10, 1.0, v110
	v_fma_f32 v62, v10, v62, v126
	v_add_f32_e32 v9, 1.0, v109
	v_fma_f32 v61, v9, v61, v125
	v_add_f32_e32 v8, 1.0, v108
	v_fma_f32 v60, v8, v60, v124
	v_cvt_pk_bf16_f32 v56, v56, v57
	v_cvt_pk_bf16_f32 v57, v58, v59
	v_cvt_pk_bf16_f32 v58, v60, v61
	v_cvt_pk_bf16_f32 v59, v62, v63
	global_store_dwordx4 v1, v[56:59], s[4:5] offset:1024
	s_waitcnt vmcnt(2)
	s_lshl_b32 s7, s11, 11
	s_add_u32 s4, s46, s7
	s_addc_u32 s5, s47, 0
	s_add_u32 s4, s4, 0x8900000
	s_addc_u32 s5, s5, 0
	v_mul_f32_e32 v67, v67, v163
	v_mul_f32_e32 v67, v83, v67
	v_mul_f32_e32 v66, v66, v163
	v_mul_f32_e32 v66, v82, v66
	v_mul_f32_e32 v65, v65, v163
	v_mul_f32_e32 v65, v81, v65
	v_mul_f32_e32 v64, v64, v163
	v_mul_f32_e32 v64, v80, v64
	v_add_f32_e32 v11, 1.0, v131
	v_fma_f32 v67, v11, v67, v147
	v_add_f32_e32 v10, 1.0, v130
	v_fma_f32 v66, v10, v66, v146
	v_add_f32_e32 v9, 1.0, v129
	v_fma_f32 v65, v9, v65, v145
	v_add_f32_e32 v8, 1.0, v128
	v_fma_f32 v64, v8, v64, v144
	v_mul_f32_e32 v71, v71, v163
	v_mul_f32_e32 v71, v87, v71
	v_mul_f32_e32 v70, v70, v163
	v_mul_f32_e32 v70, v86, v70
	v_mul_f32_e32 v69, v69, v163
	v_mul_f32_e32 v69, v85, v69
	v_mul_f32_e32 v68, v68, v163
	v_mul_f32_e32 v68, v84, v68
	v_add_f32_e32 v11, 1.0, v135
	v_fma_f32 v71, v11, v71, v151
	v_add_f32_e32 v10, 1.0, v134
	v_fma_f32 v70, v10, v70, v150
	v_add_f32_e32 v9, 1.0, v133
	v_fma_f32 v69, v9, v69, v149
	v_add_f32_e32 v8, 1.0, v132
	v_fma_f32 v68, v8, v68, v148
	v_cvt_pk_bf16_f32 v64, v64, v65
	v_cvt_pk_bf16_f32 v65, v66, v67
	v_cvt_pk_bf16_f32 v66, v68, v69
	v_cvt_pk_bf16_f32 v67, v70, v71
	global_store_dwordx4 v1, v[64:67], s[4:5]
	v_mul_f32_e32 v75, v75, v163
	v_mul_f32_e32 v75, v91, v75
	v_mul_f32_e32 v74, v74, v163
	v_mul_f32_e32 v74, v90, v74
	v_mul_f32_e32 v73, v73, v163
	v_mul_f32_e32 v73, v89, v73
	v_mul_f32_e32 v72, v72, v163
	v_mul_f32_e32 v72, v88, v72
	v_add_f32_e32 v11, 1.0, v139
	v_fma_f32 v75, v11, v75, v155
	v_add_f32_e32 v10, 1.0, v138
	v_fma_f32 v74, v10, v74, v154
	v_add_f32_e32 v9, 1.0, v137
	v_fma_f32 v73, v9, v73, v153
	v_add_f32_e32 v8, 1.0, v136
	v_fma_f32 v72, v8, v72, v152
	v_mul_f32_e32 v79, v79, v163
	v_mul_f32_e32 v79, v95, v79
	v_mul_f32_e32 v78, v78, v163
	v_mul_f32_e32 v78, v94, v78
	v_mul_f32_e32 v77, v77, v163
	v_mul_f32_e32 v77, v93, v77
	v_mul_f32_e32 v76, v76, v163
	v_mul_f32_e32 v76, v92, v76
	v_add_f32_e32 v11, 1.0, v143
	v_fma_f32 v79, v11, v79, v159
	v_add_f32_e32 v10, 1.0, v142
	v_fma_f32 v78, v10, v78, v158
	v_add_f32_e32 v9, 1.0, v141
	v_fma_f32 v77, v9, v77, v157
	v_add_f32_e32 v8, 1.0, v140
	v_fma_f32 v76, v8, v76, v156
	v_cvt_pk_bf16_f32 v72, v72, v73
	v_cvt_pk_bf16_f32 v73, v74, v75
	v_cvt_pk_bf16_f32 v74, v76, v77
	v_cvt_pk_bf16_f32 v75, v78, v79
	global_store_dwordx4 v1, v[72:75], s[4:5] offset:1024
	s_lshl_b32 s7, s6, 2
	s_add_i32 s3, s3, s7
	s_cmpk_lt_i32 s3, 0x2000
	s_cbranch_scc1 .Lnorm1_loop

.LBB0_409:
	s_add_i32 s70, s70, 1
	s_cmp_ge_i32 s70, s71
	s_mov_b64 s[4:5], -1
	s_waitcnt lgkmcnt(0)
	v_readlane_b32 s24, v239, 20
	v_readlane_b32 s25, v239, 19
	s_cbranch_scc1 .LBB0_10
	v_readlane_b32 s6, v240, 12
	v_readlane_b32 s7, v240, 13
	s_and_b64 vcc, exec, s[6:7]
	s_cbranch_vccz .LBB0_464
	s_getreg_b32 s3, hwreg(HW_REG_XCC_ID, 0, 4)
	s_waitcnt vmcnt(0)
	v_cmp_eq_u32_e32 vcc, 0, v210
	s_waitcnt vmcnt(0)
	s_barrier
	s_and_saveexec_b64 s[4:5], vcc
	s_cbranch_execz .LBB0_463
	v_readlane_b32 s6, v240, 60
	s_and_b32 s3, s3, 15
	s_lshl_b32 s3, s3, 8
	v_mov_b32_e32 v0, s6
	ds_read_b64 v[0:1], v0
	v_readlane_b32 s6, v240, 5
	v_readlane_b32 s7, v240, 6
	s_waitcnt lgkmcnt(0)
	v_cmp_ne_u32_e32 vcc, 0, v0
	s_cbranch_vccnz .Lxb_have
	s_mov_b32 s12, 0
.Lxb_census:
	global_load_dword v0, v165, s[72:73] offset:0 sc1
	global_load_dword v1, v165, s[72:73] offset:256 sc1
	global_load_dword v2, v165, s[72:73] offset:512 sc1
	global_load_dword v3, v165, s[72:73] offset:768 sc1
	global_load_dword v4, v165, s[72:73] offset:1024 sc1
	global_load_dword v5, v165, s[72:73] offset:1280 sc1
	global_load_dword v6, v165, s[72:73] offset:1536 sc1
	global_load_dword v7, v165, s[72:73] offset:1792 sc1
	global_load_dword v8, v165, s[72:73] offset:2048 sc1
	global_load_dword v9, v165, s[72:73] offset:2304 sc1
	global_load_dword v10, v165, s[72:73] offset:2560 sc1
	global_load_dword v11, v165, s[72:73] offset:2816 sc1
	global_load_dword v12, v165, s[72:73] offset:3072 sc1
	global_load_dword v13, v165, s[72:73] offset:3328 sc1
	global_load_dword v14, v165, s[72:73] offset:3584 sc1
	global_load_dword v15, v165, s[72:73] offset:3840 sc1
	s_add_u32 s10, s72, s3
	s_addc_u32 s11, s73, 0
	global_load_dword v16, v165, s[10:11] sc1
	s_mov_b32 s9, 0
	s_add_i32 s12, s12, 1
	s_waitcnt vmcnt(0)
	v_cmp_ne_u32_e32 vcc, 0, v0
	s_bcnt1_i32_b64 s8, vcc
	s_add_i32 s9, s9, s8
	v_cmp_ne_u32_e32 vcc, 0, v1
	s_bcnt1_i32_b64 s8, vcc
	s_add_i32 s9, s9, s8
	v_cmp_ne_u32_e32 vcc, 0, v2
	s_bcnt1_i32_b64 s8, vcc
	s_add_i32 s9, s9, s8
	v_cmp_ne_u32_e32 vcc, 0, v3
	s_bcnt1_i32_b64 s8, vcc
	s_add_i32 s9, s9, s8
	v_cmp_ne_u32_e32 vcc, 0, v4
	s_bcnt1_i32_b64 s8, vcc
	s_add_i32 s9, s9, s8
	v_cmp_ne_u32_e32 vcc, 0, v5
	s_bcnt1_i32_b64 s8, vcc
	s_add_i32 s9, s9, s8
	v_cmp_ne_u32_e32 vcc, 0, v6
	s_bcnt1_i32_b64 s8, vcc
	s_add_i32 s9, s9, s8
	v_cmp_ne_u32_e32 vcc, 0, v7
	s_bcnt1_i32_b64 s8, vcc
	s_add_i32 s9, s9, s8
	v_cmp_ne_u32_e32 vcc, 0, v8
	s_bcnt1_i32_b64 s8, vcc
	s_add_i32 s9, s9, s8
	v_cmp_ne_u32_e32 vcc, 0, v9
	s_bcnt1_i32_b64 s8, vcc
	s_add_i32 s9, s9, s8
	v_cmp_ne_u32_e32 vcc, 0, v10
	s_bcnt1_i32_b64 s8, vcc
	s_add_i32 s9, s9, s8
	v_cmp_ne_u32_e32 vcc, 0, v11
	s_bcnt1_i32_b64 s8, vcc
	s_add_i32 s9, s9, s8
	v_cmp_ne_u32_e32 vcc, 0, v12
	s_bcnt1_i32_b64 s8, vcc
	s_add_i32 s9, s9, s8
	v_cmp_ne_u32_e32 vcc, 0, v13
	s_bcnt1_i32_b64 s8, vcc
	s_add_i32 s9, s9, s8
	v_cmp_ne_u32_e32 vcc, 0, v14
	s_bcnt1_i32_b64 s8, vcc
	s_add_i32 s9, s9, s8
	v_cmp_ne_u32_e32 vcc, 0, v15
	s_bcnt1_i32_b64 s8, vcc
	s_add_i32 s9, s9, s8
	v_readlane_b32 s8, v239, 10
	v_add3_u32 v0, v0, v1, v2
	v_add3_u32 v3, v3, v4, v5
	v_add3_u32 v6, v6, v7, v8
	v_add3_u32 v9, v9, v10, v11
	v_add3_u32 v12, v12, v13, v14
	v_add3_u32 v0, v0, v3, v6
	v_add3_u32 v9, v9, v12, v15
	v_add_u32_e32 v0, v0, v9
	v_cmp_eq_u32_e32 vcc, s8, v0
	s_cbranch_vccnz .Lxb_census_done
	s_cmp_gt_u32 s12, 0x20000
	s_cbranch_scc1 .Lxb_census_done
	s_sleep 1
	s_branch .Lxb_census
.Lxb_census_done:
	v_readlane_b32 s8, v240, 60
	v_max_u32_e32 v0, 1, v16
	s_max_u32 s9, s9, 1
	v_mov_b32_e32 v2, s8
	v_mov_b32_e32 v1, s9
	ds_write_b64 v2, v[0:1]
.Lxb_have:
	v_readfirstlane_b32 s10, v0
	v_readfirstlane_b32 s11, v1
	s_add_u32 s12, s6, s3
	s_addc_u32 s13, s7, 0
	v_mov_b32_e32 v2, 1
	s_add_i32 s101, s101, 1
	s_mul_i32 s10, s10, s101
	s_mul_i32 s11, s11, s101
	s_waitcnt lgkmcnt(0)
	global_atomic_add v3, v196, v2, s[12:13] offset:1024 sc0
	v_readlane_b32 s8, v240, 0
	s_lshl_b32 s8, s8, 6
	s_add_u32 s8, s8, 0x4000
	s_add_u32 s14, s6, s8
	s_addc_u32 s15, s7, 0
	s_mov_b32 s9, 0
	s_waitcnt vmcnt(0)
	v_add_u32_e32 v3, 1, v3
	v_cmp_eq_u32_e32 vcc, s10, v3
	s_cbranch_vccz .Lxb_poll
	buffer_wbl2 sc1
	v_readlane_b32 s12, v240, 46
	v_readlane_b32 s13, v240, 47
	s_waitcnt vmcnt(0)
	s_nop 3
	global_atomic_add v3, v165, v2, s[12:13] sc0
	s_waitcnt vmcnt(0)
	v_add_u32_e32 v3, 1, v3
	v_cmp_eq_u32_e32 vcc, s11, v3
	s_cbranch_vccz .Lxb_poll
	s_add_u32 s12, s6, 0x4000
	s_addc_u32 s13, s7, 0
	s_mov_b64 exec, -1
	v_mbcnt_lo_u32_b32 v3, -1, 0
	v_mbcnt_hi_u32_b32 v3, -1, v3
	v_mov_b32_e32 v2, 1
	v_lshlrev_b32_e32 v3, 6, v3
	v_add_u32_e32 v4, 0x1000, v3
	v_add_u32_e32 v5, 0x2000, v3
	v_add_u32_e32 v6, 0x3000, v3
	buffer_inv sc1
	global_atomic_add v3, v2, s[12:13]
	global_atomic_add v4, v2, s[12:13]
	global_atomic_add v5, v2, s[12:13]
	global_atomic_add v6, v2, s[12:13]
	s_waitcnt vmcnt(4)
	s_mov_b64 exec, 1
	s_branch .LBB0_463
.Lxb_poll:
	global_load_dword v3, v165, s[14:15] sc1
	s_add_i32 s9, s9, 1
	s_waitcnt vmcnt(0)
	v_cmp_gt_u32_e32 vcc, s101, v3
	s_cbranch_vccz .Lxb_done
	s_cmp_gt_u32 s9, 0x40000
	s_cbranch_scc1 .Lxb_done
	s_sleep 1
	s_branch .Lxb_poll
.Lxb_done:
	buffer_inv sc1
	s_waitcnt vmcnt(0)

	.amdhsa_kernel _Z10fwd_kernel6Params
		.amdhsa_group_segment_fixed_size 0
		.amdhsa_private_segment_fixed_size 0
		.amdhsa_kernarg_size 496
		.amdhsa_user_sgpr_count 2
		.amdhsa_user_sgpr_dispatch_ptr 0
		.amdhsa_user_sgpr_queue_ptr 0
		.amdhsa_user_sgpr_kernarg_segment_ptr 1
		.amdhsa_user_sgpr_dispatch_id 0
		.amdhsa_user_sgpr_kernarg_preload_length 0
		.amdhsa_user_sgpr_kernarg_preload_offset 0
		.amdhsa_user_sgpr_private_segment_size 0
		.amdhsa_uses_dynamic_stack 0
		.amdhsa_enable_private_segment 0
		.amdhsa_system_sgpr_workgroup_id_x 1
		.amdhsa_system_sgpr_workgroup_id_y 0
		.amdhsa_system_sgpr_workgroup_id_z 0
		.amdhsa_system_sgpr_workgroup_info 0
		.amdhsa_system_vgpr_workitem_id 2
		.amdhsa_next_free_vgpr 241
		.amdhsa_next_free_sgpr 102
		.amdhsa_accum_offset 244
		.amdhsa_reserve_vcc 1
		.amdhsa_float_round_mode_32 0
		.amdhsa_float_round_mode_16_64 0
		.amdhsa_float_denorm_mode_32 3
		.amdhsa_float_denorm_mode_16_64 3
		.amdhsa_dx10_clamp 1
		.amdhsa_ieee_mode 1
		.amdhsa_fp16_overflow 0
		.amdhsa_tg_split 0
		.amdhsa_exception_fp_ieee_invalid_op 0
		.amdhsa_exception_fp_denorm_src 0
		.amdhsa_exception_fp_ieee_div_zero 0
		.amdhsa_exception_fp_ieee_overflow 0
		.amdhsa_exception_fp_ieee_underflow 0
		.amdhsa_exception_fp_ieee_inexact 0
		.amdhsa_exception_int_div_zero 0
	.end_amdhsa_kernel

amdhsa.kernels:
  - .agpr_count:     0
    .args:
      - .offset:         0
        .size:           240
        .value_kind:     by_value
      - .offset:         240
        .size:           4
        .value_kind:     hidden_block_count_x
      - .offset:         244
        .size:           4
        .value_kind:     hidden_block_count_y
      - .offset:         248
        .size:           4
        .value_kind:     hidden_block_count_z
      - .offset:         252
        .size:           2
        .value_kind:     hidden_group_size_x
      - .offset:         254
        .size:           2
        .value_kind:     hidden_group_size_y
      - .offset:         256
        .size:           2
        .value_kind:     hidden_group_size_z
      - .offset:         258
        .size:           2
        .value_kind:     hidden_remainder_x
      - .offset:         260
        .size:           2
        .value_kind:     hidden_remainder_y
      - .offset:         262
        .size:           2
        .value_kind:     hidden_remainder_z
      - .offset:         280
        .size:           8
        .value_kind:     hidden_global_offset_x
      - .offset:         288
        .size:           8
        .value_kind:     hidden_global_offset_y
      - .offset:         296
        .size:           8
        .value_kind:     hidden_global_offset_z
      - .offset:         304
        .size:           2
        .value_kind:     hidden_grid_dims
      - .offset:         328
        .size:           8
        .value_kind:     hidden_multigrid_sync_arg
      - .offset:         360
        .size:           4
        .value_kind:     hidden_dynamic_lds_size
    .group_segment_fixed_size: 0
    .kernarg_segment_align: 8
    .kernarg_segment_size: 496
    .language:       OpenCL C
    .language_version:
      - 2
      - 0
    .max_flat_workgroup_size: 512
    .name:           _Z10fwd_kernel6Params
    .private_segment_fixed_size: 0
    .sgpr_count:     108
    .sgpr_spill_count: 191
    .symbol:         _Z10fwd_kernel6Params.kd
    .uniform_work_group_size: 1
    .uses_dynamic_stack: false
    .vgpr_count:     241
    .vgpr_spill_count: 0
    .wavefront_size: 64
